# conv phase: all 32 row loads of an item in flight (was 1 load per wave); rcp instead of IEEE div in sigmoid/silu; batched residual epilogue loads; mlaprep gains hoisted
# speedup vs baseline: 1.0498x; 1.0498x over previous
; __device__ __forceinline__ u32x2 pk4(f32x4 v) { u32x2 w; w.x = pk2(v[0], v[1]); w.y = pk2(v[2], v[3]); return w; }
; __device__ __forceinline__ float sigmoidf_(float z) { return 1.f / (1.f + __expf(-z)); }
;     __device__ __forceinline__ void operator()(const f32x4 (&acc)[2][2][4][2], const Unit& u, int wr, int wc, int fr, int fq) const {
;     ...
;             const bool isb = pn >= 19; bf16_t* G = isb ? GB : GA; const int c0 = (pn - (isb ? 19 : 15)) * 256 + lc0;
; #pragma unroll
;             for (int ai = 0; ai < 2; ++ai)
; #pragma unroll
;                 for (int m = 0; m < 4; ++m) { bf16_t* rp = G + (size_t)(pm * 256 + ai * 128 + m * 16 + lr0) * 1024 + c0;
; #pragma unroll
;                     for (int bj = 0; bj < 2; ++bj)
; #pragma unroll
;                         for (int n = 0; n < 2; ++n) { const f32x4 z = acc[ai][bj][m][n]; f32x4 sg; sg[0] = sigmoidf_(z[0]); sg[1] = sigmoidf_(z[1]); sg[2] = sigmoidf_(z[2]); sg[3] = sigmoidf_(z[3]);
;                             *(u32x2*)(rp + bj * 128 + n * 16) = pk4(sg); } }
.LBB0_208:
	s_andn2_b64 vcc, exec, s[0:1]
	s_cbranch_vccnz .LBB0_210
	s_cmp_gt_u32 s59, 18
	s_cselect_b64 s[0:1], -1, 0
	s_and_b64 s[0:1], s[0:1], exec
	s_mov_b32 s0, 0x27740000
	v_mul_f32_e32 v128, 0xbfb8aa3b, v124
	s_cselect_b32 s0, s0, 0x236c0000
	v_exp_f32_e32 v128, v128
	s_cselect_b32 s16, 0xffffffed, -15
	s_add_u32 s0, s42, s0
	s_addc_u32 s1, s43, 0
	s_add_i32 s16, s16, s59
	v_lshl_or_b32 v166, s16, 8, v136
	v_ashrrev_i32_e32 v167, 31, v166
	v_add_f32_e32 v128, 1.0, v128
	v_lshl_add_u64 v[166:167], v[166:167], 1, s[0:1]
	v_lshl_add_u32 v168, s57, 8, v134
	v_ashrrev_i32_e32 v169, 31, v168
	v_lshlrev_b64 v[170:171], 11, v[168:169]
	v_rcp_f32_e32 v128, v128
	s_nop 0
	v_mul_f32_e32 v163, 0xbfb8aa3b, v125
	v_exp_f32_e32 v163, v163
	v_lshl_add_u64 v[170:171], v[166:167], 0, v[170:171]
	v_add_f32_e32 v163, 1.0, v163
	v_rcp_f32_e32 v163, v163
	s_nop 0
	v_mul_f32_e32 v165, 0xbfb8aa3b, v126
	v_exp_f32_e32 v165, v165
	s_nop 0
	v_add_f32_e32 v165, 1.0, v165
	v_rcp_f32_e32 v165, v165
	s_nop 0
	v_mul_f32_e32 v169, 0xbfb8aa3b, v127
	v_exp_f32_e32 v169, v169
	s_nop 0
	v_add_f32_e32 v169, 1.0, v169
	v_rcp_f32_e32 v169, v169
	s_nop 0
	v_cvt_pk_bf16_f32 v172, v128, v163
	v_mul_f32_e32 v128, 0xbfb8aa3b, v120
	v_exp_f32_e32 v128, v128
	v_cvt_pk_bf16_f32 v173, v165, v169
	global_store_dwordx2 v[170:171], v[172:173], off
	v_add_f32_e32 v128, 1.0, v128
	v_rcp_f32_e32 v128, v128
	s_nop 0
	v_mul_f32_e32 v163, 0xbfb8aa3b, v121
	v_exp_f32_e32 v163, v163
	s_nop 0
	v_add_f32_e32 v163, 1.0, v163
	v_rcp_f32_e32 v163, v163
	s_nop 0
	v_mul_f32_e32 v165, 0xbfb8aa3b, v122
	v_exp_f32_e32 v165, v165
	s_nop 0
	v_add_f32_e32 v165, 1.0, v165
	v_rcp_f32_e32 v165, v165
	s_nop 0
	v_mul_f32_e32 v169, 0xbfb8aa3b, v123
	v_exp_f32_e32 v169, v169
	s_nop 0
	v_add_f32_e32 v169, 1.0, v169
	v_rcp_f32_e32 v169, v169
	s_nop 0
	v_cvt_pk_bf16_f32 v172, v128, v163
	v_mul_f32_e32 v128, 0xbfb8aa3b, v116
	v_exp_f32_e32 v128, v128
	v_cvt_pk_bf16_f32 v173, v165, v169
	global_store_dwordx2 v[170:171], v[172:173], off offset:32
	v_add_f32_e32 v128, 1.0, v128
	v_rcp_f32_e32 v128, v128
	s_nop 0
	v_mul_f32_e32 v163, 0xbfb8aa3b, v117
	v_exp_f32_e32 v163, v163
	s_nop 0
	v_add_f32_e32 v163, 1.0, v163
	v_rcp_f32_e32 v163, v163
	s_nop 0
	v_mul_f32_e32 v165, 0xbfb8aa3b, v118
	v_exp_f32_e32 v165, v165
	s_nop 0
	v_add_f32_e32 v165, 1.0, v165
	v_rcp_f32_e32 v165, v165
	s_nop 0
	v_mul_f32_e32 v169, 0xbfb8aa3b, v119
	v_exp_f32_e32 v169, v169
	s_nop 0
	v_add_f32_e32 v169, 1.0, v169
	v_rcp_f32_e32 v169, v169
	s_nop 0
	v_cvt_pk_bf16_f32 v172, v128, v163
	v_mul_f32_e32 v128, 0xbfb8aa3b, v112
	v_exp_f32_e32 v128, v128
	v_cvt_pk_bf16_f32 v173, v165, v169
	global_store_dwordx2 v[170:171], v[172:173], off offset:256
	v_add_f32_e32 v128, 1.0, v128
	v_rcp_f32_e32 v128, v128
	s_nop 0
	v_mul_f32_e32 v163, 0xbfb8aa3b, v113
	v_exp_f32_e32 v163, v163
	s_nop 0
	v_add_f32_e32 v163, 1.0, v163
	v_rcp_f32_e32 v163, v163
	s_nop 0
	v_mul_f32_e32 v165, 0xbfb8aa3b, v114
	v_exp_f32_e32 v165, v165
	s_nop 0
	v_add_f32_e32 v165, 1.0, v165
	v_rcp_f32_e32 v165, v165
	s_nop 0
	v_mul_f32_e32 v169, 0xbfb8aa3b, v115
	v_exp_f32_e32 v169, v169
	s_nop 0
	v_add_f32_e32 v169, 1.0, v169
	v_rcp_f32_e32 v169, v169
	s_nop 0
	v_cvt_pk_bf16_f32 v172, v128, v163
	v_mul_f32_e32 v128, 0xbfb8aa3b, v108
	v_exp_f32_e32 v128, v128
	v_cvt_pk_bf16_f32 v173, v165, v169
	global_store_dwordx2 v[170:171], v[172:173], off offset:288
	v_or_b32_e32 v170, 16, v168
	v_add_f32_e32 v128, 1.0, v128
	v_ashrrev_i32_e32 v171, 31, v170
	v_lshlrev_b64 v[170:171], 11, v[170:171]
	v_lshl_add_u64 v[170:171], v[166:167], 0, v[170:171]
	v_rcp_f32_e32 v128, v128
	s_nop 0
	v_mul_f32_e32 v163, 0xbfb8aa3b, v109
	v_exp_f32_e32 v163, v163
	s_nop 0
	v_add_f32_e32 v163, 1.0, v163
	v_rcp_f32_e32 v163, v163
	s_nop 0
	v_mul_f32_e32 v165, 0xbfb8aa3b, v110
	v_exp_f32_e32 v165, v165
	s_nop 0
	v_add_f32_e32 v165, 1.0, v165
	v_rcp_f32_e32 v165, v165
	s_nop 0
	v_mul_f32_e32 v169, 0xbfb8aa3b, v111
	v_exp_f32_e32 v169, v169
	s_nop 0
	v_add_f32_e32 v169, 1.0, v169
	v_rcp_f32_e32 v169, v169
	s_nop 0
	v_cvt_pk_bf16_f32 v172, v128, v163
	v_mul_f32_e32 v128, 0xbfb8aa3b, v104
	v_exp_f32_e32 v128, v128
	v_cvt_pk_bf16_f32 v173, v165, v169
	global_store_dwordx2 v[170:171], v[172:173], off
	v_add_f32_e32 v128, 1.0, v128
	v_rcp_f32_e32 v128, v128
	s_nop 0
	v_mul_f32_e32 v163, 0xbfb8aa3b, v105
	v_exp_f32_e32 v163, v163
	s_nop 0
	v_add_f32_e32 v163, 1.0, v163
	v_rcp_f32_e32 v163, v163
	s_nop 0
	v_mul_f32_e32 v165, 0xbfb8aa3b, v106
	v_exp_f32_e32 v165, v165
	s_nop 0
	v_add_f32_e32 v165, 1.0, v165
	v_rcp_f32_e32 v165, v165
	s_nop 0
	v_mul_f32_e32 v169, 0xbfb8aa3b, v107
	v_exp_f32_e32 v169, v169
	s_nop 0
	v_add_f32_e32 v169, 1.0, v169
	v_rcp_f32_e32 v169, v169
	s_nop 0
	v_cvt_pk_bf16_f32 v172, v128, v163
	v_mul_f32_e32 v128, 0xbfb8aa3b, v100
	v_exp_f32_e32 v128, v128
	v_cvt_pk_bf16_f32 v173, v165, v169
	global_store_dwordx2 v[170:171], v[172:173], off offset:32
	v_add_f32_e32 v128, 1.0, v128
	v_rcp_f32_e32 v128, v128
	s_nop 0
	v_mul_f32_e32 v163, 0xbfb8aa3b, v101
	v_exp_f32_e32 v163, v163
	s_nop 0
	v_add_f32_e32 v163, 1.0, v163
	v_rcp_f32_e32 v163, v163
	s_nop 0
	v_mul_f32_e32 v165, 0xbfb8aa3b, v102
	v_exp_f32_e32 v165, v165
	s_nop 0
	v_add_f32_e32 v165, 1.0, v165
	v_rcp_f32_e32 v165, v165
	s_nop 0
	v_mul_f32_e32 v169, 0xbfb8aa3b, v103
	v_exp_f32_e32 v169, v169
	s_nop 0
	v_add_f32_e32 v169, 1.0, v169
	v_rcp_f32_e32 v169, v169
	s_nop 0
	v_cvt_pk_bf16_f32 v172, v128, v163
	v_mul_f32_e32 v128, 0xbfb8aa3b, v96
	v_exp_f32_e32 v128, v128
	v_cvt_pk_bf16_f32 v173, v165, v169
	global_store_dwordx2 v[170:171], v[172:173], off offset:256
	v_add_f32_e32 v128, 1.0, v128
	v_rcp_f32_e32 v128, v128
	s_nop 0
	v_mul_f32_e32 v163, 0xbfb8aa3b, v97
; __device__ __forceinline__ u32x2 pk4(f32x4 v) { u32x2 w; w.x = pk2(v[0], v[1]); w.y = pk2(v[2], v[3]); return w; }
; __device__ __forceinline__ float sigmoidf_(float z) { return 1.f / (1.f + __expf(-z)); }
;     __device__ __forceinline__ void operator()(const f32x4 (&acc)[2][2][4][2], const Unit& u, int wr, int wc, int fr, int fq) const {
;     ...
;             const bool isb = pn >= 19; bf16_t* G = isb ? GB : GA; const int c0 = (pn - (isb ? 19 : 15)) * 256 + lc0;
; #pragma unroll
;             for (int ai = 0; ai < 2; ++ai)
; #pragma unroll
;                 for (int m = 0; m < 4; ++m) { bf16_t* rp = G + (size_t)(pm * 256 + ai * 128 + m * 16 + lr0) * 1024 + c0;
; #pragma unroll
;                     for (int bj = 0; bj < 2; ++bj)
; #pragma unroll
;                         for (int n = 0; n < 2; ++n) { const f32x4 z = acc[ai][bj][m][n]; f32x4 sg; sg[0] = sigmoidf_(z[0]); sg[1] = sigmoidf_(z[1]); sg[2] = sigmoidf_(z[2]); sg[3] = sigmoidf_(z[3]);
;                             *(u32x2*)(rp + bj * 128 + n * 16) = pk4(sg); } }
	v_exp_f32_e32 v163, v163
	s_nop 0
	v_add_f32_e32 v163, 1.0, v163
	v_rcp_f32_e32 v163, v163
	s_nop 0
	v_mul_f32_e32 v165, 0xbfb8aa3b, v98
	v_exp_f32_e32 v165, v165
	s_nop 0
	v_add_f32_e32 v165, 1.0, v165
	v_rcp_f32_e32 v165, v165
	s_nop 0
	v_mul_f32_e32 v169, 0xbfb8aa3b, v99
	v_exp_f32_e32 v169, v169
	s_nop 0
	v_add_f32_e32 v169, 1.0, v169
	v_rcp_f32_e32 v169, v169
	s_nop 0
	v_cvt_pk_bf16_f32 v172, v128, v163
	v_mul_f32_e32 v128, 0xbfb8aa3b, v92
	v_exp_f32_e32 v128, v128
	v_cvt_pk_bf16_f32 v173, v165, v169
	global_store_dwordx2 v[170:171], v[172:173], off offset:288
	v_or_b32_e32 v170, 32, v168
	v_add_f32_e32 v128, 1.0, v128
	v_ashrrev_i32_e32 v171, 31, v170
	v_lshlrev_b64 v[170:171], 11, v[170:171]
	v_lshl_add_u64 v[170:171], v[166:167], 0, v[170:171]
	v_rcp_f32_e32 v128, v128
	s_nop 0
	v_mul_f32_e32 v163, 0xbfb8aa3b, v93
	v_exp_f32_e32 v163, v163
	s_nop 0
	v_add_f32_e32 v163, 1.0, v163
	v_rcp_f32_e32 v163, v163
	s_nop 0
	v_mul_f32_e32 v165, 0xbfb8aa3b, v94
	v_exp_f32_e32 v165, v165
	s_nop 0
	v_add_f32_e32 v165, 1.0, v165
	v_rcp_f32_e32 v165, v165
	s_nop 0
	v_mul_f32_e32 v169, 0xbfb8aa3b, v95
	v_exp_f32_e32 v169, v169
	s_nop 0
	v_add_f32_e32 v169, 1.0, v169
	v_rcp_f32_e32 v169, v169
	s_nop 0
	v_cvt_pk_bf16_f32 v172, v128, v163
	v_mul_f32_e32 v128, 0xbfb8aa3b, v88
	v_exp_f32_e32 v128, v128
	v_cvt_pk_bf16_f32 v173, v165, v169
	global_store_dwordx2 v[170:171], v[172:173], off
	v_add_f32_e32 v128, 1.0, v128
	v_rcp_f32_e32 v128, v128
	s_nop 0
	v_mul_f32_e32 v163, 0xbfb8aa3b, v89
	v_exp_f32_e32 v163, v163
	s_nop 0
	v_add_f32_e32 v163, 1.0, v163
	v_rcp_f32_e32 v163, v163
	s_nop 0
	v_mul_f32_e32 v165, 0xbfb8aa3b, v90
	v_exp_f32_e32 v165, v165
	s_nop 0
	v_add_f32_e32 v165, 1.0, v165
	v_rcp_f32_e32 v165, v165
	s_nop 0
	v_mul_f32_e32 v169, 0xbfb8aa3b, v91
	v_exp_f32_e32 v169, v169
	s_nop 0
	v_add_f32_e32 v169, 1.0, v169
	v_rcp_f32_e32 v169, v169
	s_nop 0
	v_cvt_pk_bf16_f32 v172, v128, v163
	v_mul_f32_e32 v128, 0xbfb8aa3b, v84
	v_exp_f32_e32 v128, v128
	v_cvt_pk_bf16_f32 v173, v165, v169
	global_store_dwordx2 v[170:171], v[172:173], off offset:32
	v_add_f32_e32 v128, 1.0, v128
	v_rcp_f32_e32 v128, v128
	s_nop 0
	v_mul_f32_e32 v163, 0xbfb8aa3b, v85
	v_exp_f32_e32 v163, v163
	s_nop 0
	v_add_f32_e32 v163, 1.0, v163
	v_rcp_f32_e32 v163, v163
	s_nop 0
	v_mul_f32_e32 v165, 0xbfb8aa3b, v86
	v_exp_f32_e32 v165, v165
	s_nop 0
	v_add_f32_e32 v165, 1.0, v165
	v_rcp_f32_e32 v165, v165
	s_nop 0
	v_mul_f32_e32 v169, 0xbfb8aa3b, v87
	v_exp_f32_e32 v169, v169
	s_nop 0
	v_add_f32_e32 v169, 1.0, v169
	v_rcp_f32_e32 v169, v169
	s_nop 0
	v_cvt_pk_bf16_f32 v172, v128, v163
	v_mul_f32_e32 v128, 0xbfb8aa3b, v80
	v_exp_f32_e32 v128, v128
	v_cvt_pk_bf16_f32 v173, v165, v169
	global_store_dwordx2 v[170:171], v[172:173], off offset:256
	v_add_f32_e32 v128, 1.0, v128
	v_rcp_f32_e32 v128, v128
	s_nop 0
	v_mul_f32_e32 v163, 0xbfb8aa3b, v81
	v_exp_f32_e32 v163, v163
	s_nop 0
	v_add_f32_e32 v163, 1.0, v163
	v_rcp_f32_e32 v163, v163
	s_nop 0
	v_mul_f32_e32 v165, 0xbfb8aa3b, v82
	v_exp_f32_e32 v165, v165
	s_nop 0
	v_add_f32_e32 v165, 1.0, v165
	v_rcp_f32_e32 v165, v165
	s_nop 0
	v_mul_f32_e32 v169, 0xbfb8aa3b, v83
	v_exp_f32_e32 v169, v169
	s_nop 0
	v_add_f32_e32 v169, 1.0, v169
	v_rcp_f32_e32 v169, v169
	s_nop 0
	v_cvt_pk_bf16_f32 v172, v128, v163
	v_mul_f32_e32 v128, 0xbfb8aa3b, v76
	v_exp_f32_e32 v128, v128
	v_cvt_pk_bf16_f32 v173, v165, v169
	global_store_dwordx2 v[170:171], v[172:173], off offset:288
	v_or_b32_e32 v170, 48, v168
	v_add_f32_e32 v128, 1.0, v128
	v_ashrrev_i32_e32 v171, 31, v170
	v_lshlrev_b64 v[170:171], 11, v[170:171]
	v_lshl_add_u64 v[170:171], v[166:167], 0, v[170:171]
	v_rcp_f32_e32 v128, v128
	s_nop 0
	v_mul_f32_e32 v163, 0xbfb8aa3b, v77
	v_exp_f32_e32 v163, v163
	s_nop 0
	v_add_f32_e32 v163, 1.0, v163
	v_rcp_f32_e32 v163, v163
	s_nop 0
	v_mul_f32_e32 v165, 0xbfb8aa3b, v78
	v_exp_f32_e32 v165, v165
	s_nop 0
	v_add_f32_e32 v165, 1.0, v165
	v_rcp_f32_e32 v165, v165
	s_nop 0
	v_mul_f32_e32 v169, 0xbfb8aa3b, v79
	v_exp_f32_e32 v169, v169
	s_nop 0
	v_add_f32_e32 v169, 1.0, v169
	v_rcp_f32_e32 v169, v169
	s_nop 0
	v_cvt_pk_bf16_f32 v172, v128, v163
	v_mul_f32_e32 v128, 0xbfb8aa3b, v72
	v_exp_f32_e32 v128, v128
	v_cvt_pk_bf16_f32 v173, v165, v169
	global_store_dwordx2 v[170:171], v[172:173], off
	v_add_f32_e32 v128, 1.0, v128
	v_rcp_f32_e32 v128, v128
	s_nop 0
	v_mul_f32_e32 v163, 0xbfb8aa3b, v73
	v_exp_f32_e32 v163, v163
	s_nop 0
	v_add_f32_e32 v163, 1.0, v163
	v_rcp_f32_e32 v163, v163
	s_nop 0
	v_mul_f32_e32 v165, 0xbfb8aa3b, v74
	v_exp_f32_e32 v165, v165
	s_nop 0
	v_add_f32_e32 v165, 1.0, v165
	v_rcp_f32_e32 v165, v165
	s_nop 0
	v_mul_f32_e32 v169, 0xbfb8aa3b, v75
	v_exp_f32_e32 v169, v169
	s_nop 0
	v_add_f32_e32 v169, 1.0, v169
	v_rcp_f32_e32 v169, v169
	s_nop 0
	v_cvt_pk_bf16_f32 v172, v128, v163
	v_mul_f32_e32 v128, 0xbfb8aa3b, v68
	v_exp_f32_e32 v128, v128
	v_cvt_pk_bf16_f32 v173, v165, v169
	global_store_dwordx2 v[170:171], v[172:173], off offset:32
	v_add_f32_e32 v128, 1.0, v128
	v_rcp_f32_e32 v128, v128
	s_nop 0
	v_mul_f32_e32 v163, 0xbfb8aa3b, v69
	v_exp_f32_e32 v163, v163
	s_nop 0
	v_add_f32_e32 v163, 1.0, v163
	v_rcp_f32_e32 v163, v163
	s_nop 0
	v_mul_f32_e32 v165, 0xbfb8aa3b, v70
	v_exp_f32_e32 v165, v165
	s_nop 0
	v_add_f32_e32 v165, 1.0, v165
	v_rcp_f32_e32 v165, v165
	s_nop 0
	v_mul_f32_e32 v169, 0xbfb8aa3b, v71
	v_exp_f32_e32 v169, v169
	s_nop 0
	v_add_f32_e32 v169, 1.0, v169
	v_rcp_f32_e32 v169, v169
	s_nop 0
	v_cvt_pk_bf16_f32 v172, v128, v163
	v_mul_f32_e32 v128, 0xbfb8aa3b, v64
	v_exp_f32_e32 v128, v128
	v_cvt_pk_bf16_f32 v173, v165, v169
	global_store_dwordx2 v[170:171], v[172:173], off offset:256
	v_add_f32_e32 v128, 1.0, v128
; __device__ __forceinline__ u32x2 pk4(f32x4 v) { u32x2 w; w.x = pk2(v[0], v[1]); w.y = pk2(v[2], v[3]); return w; }
; __device__ __forceinline__ float sigmoidf_(float z) { return 1.f / (1.f + __expf(-z)); }
;     __device__ __forceinline__ void operator()(const f32x4 (&acc)[2][2][4][2], const Unit& u, int wr, int wc, int fr, int fq) const {
;     ...
;             const bool isb = pn >= 19; bf16_t* G = isb ? GB : GA; const int c0 = (pn - (isb ? 19 : 15)) * 256 + lc0;
; #pragma unroll
;             for (int ai = 0; ai < 2; ++ai)
; #pragma unroll
;                 for (int m = 0; m < 4; ++m) { bf16_t* rp = G + (size_t)(pm * 256 + ai * 128 + m * 16 + lr0) * 1024 + c0;
; #pragma unroll
;                     for (int bj = 0; bj < 2; ++bj)
; #pragma unroll
;                         for (int n = 0; n < 2; ++n) { const f32x4 z = acc[ai][bj][m][n]; f32x4 sg; sg[0] = sigmoidf_(z[0]); sg[1] = sigmoidf_(z[1]); sg[2] = sigmoidf_(z[2]); sg[3] = sigmoidf_(z[3]);
;                             *(u32x2*)(rp + bj * 128 + n * 16) = pk4(sg); } }
	v_rcp_f32_e32 v128, v128
	s_nop 0
	v_mul_f32_e32 v163, 0xbfb8aa3b, v65
	v_exp_f32_e32 v163, v163
	s_nop 0
	v_add_f32_e32 v163, 1.0, v163
	v_rcp_f32_e32 v163, v163
	s_nop 0
	v_mul_f32_e32 v165, 0xbfb8aa3b, v66
	v_exp_f32_e32 v165, v165
	s_nop 0
	v_add_f32_e32 v165, 1.0, v165
	v_rcp_f32_e32 v165, v165
	s_nop 0
	v_mul_f32_e32 v169, 0xbfb8aa3b, v67
	v_exp_f32_e32 v169, v169
	s_nop 0
	v_add_f32_e32 v169, 1.0, v169
	v_rcp_f32_e32 v169, v169
	s_nop 0
	v_cvt_pk_bf16_f32 v172, v128, v163
	v_mul_f32_e32 v128, 0xbfb8aa3b, v60
	v_exp_f32_e32 v128, v128
	v_cvt_pk_bf16_f32 v173, v165, v169
	global_store_dwordx2 v[170:171], v[172:173], off offset:288
	v_add_u32_e32 v170, 0x80, v168
	v_add_f32_e32 v128, 1.0, v128
	v_ashrrev_i32_e32 v171, 31, v170
	v_lshlrev_b64 v[170:171], 11, v[170:171]
	v_lshl_add_u64 v[170:171], v[166:167], 0, v[170:171]
	v_rcp_f32_e32 v128, v128
	s_nop 0
	v_mul_f32_e32 v163, 0xbfb8aa3b, v61
	v_exp_f32_e32 v163, v163
	s_nop 0
	v_add_f32_e32 v163, 1.0, v163
	v_rcp_f32_e32 v163, v163
	s_nop 0
	v_mul_f32_e32 v165, 0xbfb8aa3b, v62
	v_exp_f32_e32 v165, v165
	s_nop 0
	v_add_f32_e32 v165, 1.0, v165
	v_rcp_f32_e32 v165, v165
	s_nop 0
	v_mul_f32_e32 v169, 0xbfb8aa3b, v63
	v_exp_f32_e32 v169, v169
	s_nop 0
	v_add_f32_e32 v169, 1.0, v169
	v_rcp_f32_e32 v169, v169
	s_nop 0
	v_cvt_pk_bf16_f32 v172, v128, v163
	v_mul_f32_e32 v128, 0xbfb8aa3b, v56
	v_exp_f32_e32 v128, v128
	v_cvt_pk_bf16_f32 v173, v165, v169
	global_store_dwordx2 v[170:171], v[172:173], off
	v_add_f32_e32 v128, 1.0, v128
	v_rcp_f32_e32 v128, v128
	s_nop 0
	v_mul_f32_e32 v163, 0xbfb8aa3b, v57
	v_exp_f32_e32 v163, v163
	s_nop 0
	v_add_f32_e32 v163, 1.0, v163
	v_rcp_f32_e32 v163, v163
	s_nop 0
	v_mul_f32_e32 v165, 0xbfb8aa3b, v58
	v_exp_f32_e32 v165, v165
	s_nop 0
	v_add_f32_e32 v165, 1.0, v165
	v_rcp_f32_e32 v165, v165
	s_nop 0
	v_mul_f32_e32 v169, 0xbfb8aa3b, v59
	v_exp_f32_e32 v169, v169
	s_nop 0
	v_add_f32_e32 v169, 1.0, v169
	v_rcp_f32_e32 v169, v169
	s_nop 0
	v_cvt_pk_bf16_f32 v172, v128, v163
	v_mul_f32_e32 v128, 0xbfb8aa3b, v52
	v_exp_f32_e32 v128, v128
	v_cvt_pk_bf16_f32 v173, v165, v169
	global_store_dwordx2 v[170:171], v[172:173], off offset:32
	v_add_f32_e32 v128, 1.0, v128
	v_rcp_f32_e32 v128, v128
	s_nop 0
	v_mul_f32_e32 v163, 0xbfb8aa3b, v53
	v_exp_f32_e32 v163, v163
	s_nop 0
	v_add_f32_e32 v163, 1.0, v163
	v_rcp_f32_e32 v163, v163
	s_nop 0
	v_mul_f32_e32 v165, 0xbfb8aa3b, v54
	v_exp_f32_e32 v165, v165
	s_nop 0
	v_add_f32_e32 v165, 1.0, v165
	v_rcp_f32_e32 v165, v165
	s_nop 0
	v_mul_f32_e32 v169, 0xbfb8aa3b, v55
	v_exp_f32_e32 v169, v169
	s_nop 0
	v_add_f32_e32 v169, 1.0, v169
	v_rcp_f32_e32 v169, v169
	s_nop 0
	v_cvt_pk_bf16_f32 v172, v128, v163
	v_mul_f32_e32 v128, 0xbfb8aa3b, v48
	v_exp_f32_e32 v128, v128
	v_cvt_pk_bf16_f32 v173, v165, v169
	global_store_dwordx2 v[170:171], v[172:173], off offset:256
	v_add_f32_e32 v128, 1.0, v128
	v_rcp_f32_e32 v128, v128
	s_nop 0
	v_mul_f32_e32 v163, 0xbfb8aa3b, v49
	v_exp_f32_e32 v163, v163
	s_nop 0
	v_add_f32_e32 v163, 1.0, v163
	v_rcp_f32_e32 v163, v163
	s_nop 0
	v_mul_f32_e32 v165, 0xbfb8aa3b, v50
	v_exp_f32_e32 v165, v165
	s_nop 0
	v_add_f32_e32 v165, 1.0, v165
	v_rcp_f32_e32 v165, v165
	s_nop 0
	v_mul_f32_e32 v169, 0xbfb8aa3b, v51
	v_exp_f32_e32 v169, v169
	s_nop 0
	v_add_f32_e32 v169, 1.0, v169
	v_rcp_f32_e32 v169, v169
	s_nop 0
	v_cvt_pk_bf16_f32 v172, v128, v163
	v_mul_f32_e32 v128, 0xbfb8aa3b, v44
	v_exp_f32_e32 v128, v128
	v_cvt_pk_bf16_f32 v173, v165, v169
	global_store_dwordx2 v[170:171], v[172:173], off offset:288
	v_add_u32_e32 v170, 0x90, v168
	v_add_f32_e32 v128, 1.0, v128
	v_ashrrev_i32_e32 v171, 31, v170
	v_lshlrev_b64 v[170:171], 11, v[170:171]
	v_lshl_add_u64 v[170:171], v[166:167], 0, v[170:171]
	v_rcp_f32_e32 v128, v128
	s_nop 0
	v_mul_f32_e32 v163, 0xbfb8aa3b, v45
	v_exp_f32_e32 v163, v163
	s_nop 0
	v_add_f32_e32 v163, 1.0, v163
	v_rcp_f32_e32 v163, v163
	s_nop 0
	v_mul_f32_e32 v165, 0xbfb8aa3b, v46
	v_exp_f32_e32 v165, v165
	s_nop 0
	v_add_f32_e32 v165, 1.0, v165
	v_rcp_f32_e32 v165, v165
	s_nop 0
	v_mul_f32_e32 v169, 0xbfb8aa3b, v47
	v_exp_f32_e32 v169, v169
	s_nop 0
	v_add_f32_e32 v169, 1.0, v169
	v_rcp_f32_e32 v169, v169
	s_nop 0
	v_cvt_pk_bf16_f32 v172, v128, v163
	v_mul_f32_e32 v128, 0xbfb8aa3b, v40
	v_exp_f32_e32 v128, v128
	v_cvt_pk_bf16_f32 v173, v165, v169
	global_store_dwordx2 v[170:171], v[172:173], off
	v_add_f32_e32 v128, 1.0, v128
	v_rcp_f32_e32 v128, v128
	s_nop 0
	v_mul_f32_e32 v163, 0xbfb8aa3b, v41
	v_exp_f32_e32 v163, v163
	s_nop 0
	v_add_f32_e32 v163, 1.0, v163
	v_rcp_f32_e32 v163, v163
	s_nop 0
	v_mul_f32_e32 v165, 0xbfb8aa3b, v42
	v_exp_f32_e32 v165, v165
	s_nop 0
	v_add_f32_e32 v165, 1.0, v165
	v_rcp_f32_e32 v165, v165
	s_nop 0
	v_mul_f32_e32 v169, 0xbfb8aa3b, v43
	v_exp_f32_e32 v169, v169
	s_nop 0
	v_add_f32_e32 v169, 1.0, v169
	v_rcp_f32_e32 v169, v169
	s_nop 0
	v_cvt_pk_bf16_f32 v172, v128, v163
	v_mul_f32_e32 v128, 0xbfb8aa3b, v36
	v_exp_f32_e32 v128, v128
	v_cvt_pk_bf16_f32 v173, v165, v169
	global_store_dwordx2 v[170:171], v[172:173], off offset:32
	v_add_f32_e32 v128, 1.0, v128
	v_rcp_f32_e32 v128, v128
	s_nop 0
	v_mul_f32_e32 v163, 0xbfb8aa3b, v37
	v_exp_f32_e32 v163, v163
	s_nop 0
	v_add_f32_e32 v163, 1.0, v163
	v_rcp_f32_e32 v163, v163
	s_nop 0
	v_mul_f32_e32 v165, 0xbfb8aa3b, v38
	v_exp_f32_e32 v165, v165
	s_nop 0
	v_add_f32_e32 v165, 1.0, v165
	v_rcp_f32_e32 v165, v165
	s_nop 0
	v_mul_f32_e32 v169, 0xbfb8aa3b, v39
	v_exp_f32_e32 v169, v169
	s_nop 0
	v_add_f32_e32 v169, 1.0, v169
	v_rcp_f32_e32 v169, v169
	s_nop 0
	v_cvt_pk_bf16_f32 v172, v128, v163
	v_mul_f32_e32 v128, 0xbfb8aa3b, v32
	v_exp_f32_e32 v128, v128
	v_cvt_pk_bf16_f32 v173, v165, v169
; __device__ __forceinline__ u32x2 pk4(f32x4 v) { u32x2 w; w.x = pk2(v[0], v[1]); w.y = pk2(v[2], v[3]); return w; }
; __device__ __forceinline__ float sigmoidf_(float z) { return 1.f / (1.f + __expf(-z)); }
;     __device__ __forceinline__ void operator()(const f32x4 (&acc)[2][2][4][2], const Unit& u, int wr, int wc, int fr, int fq) const {
;     ...
;             const bool isb = pn >= 19; bf16_t* G = isb ? GB : GA; const int c0 = (pn - (isb ? 19 : 15)) * 256 + lc0;
; #pragma unroll
;             for (int ai = 0; ai < 2; ++ai)
; #pragma unroll
;                 for (int m = 0; m < 4; ++m) { bf16_t* rp = G + (size_t)(pm * 256 + ai * 128 + m * 16 + lr0) * 1024 + c0;
; #pragma unroll
;                     for (int bj = 0; bj < 2; ++bj)
; #pragma unroll
;                         for (int n = 0; n < 2; ++n) { const f32x4 z = acc[ai][bj][m][n]; f32x4 sg; sg[0] = sigmoidf_(z[0]); sg[1] = sigmoidf_(z[1]); sg[2] = sigmoidf_(z[2]); sg[3] = sigmoidf_(z[3]);
;                             *(u32x2*)(rp + bj * 128 + n * 16) = pk4(sg); } }
	global_store_dwordx2 v[170:171], v[172:173], off offset:256
	v_add_f32_e32 v128, 1.0, v128
	v_rcp_f32_e32 v128, v128
	s_nop 0
	v_mul_f32_e32 v163, 0xbfb8aa3b, v33
	v_exp_f32_e32 v163, v163
	s_nop 0
	v_add_f32_e32 v163, 1.0, v163
	v_rcp_f32_e32 v163, v163
	s_nop 0
	v_mul_f32_e32 v165, 0xbfb8aa3b, v34
	v_exp_f32_e32 v165, v165
	s_nop 0
	v_add_f32_e32 v165, 1.0, v165
	v_rcp_f32_e32 v165, v165
	s_nop 0
	v_mul_f32_e32 v169, 0xbfb8aa3b, v35
	v_exp_f32_e32 v169, v169
	s_nop 0
	v_add_f32_e32 v169, 1.0, v169
	v_rcp_f32_e32 v169, v169
	s_nop 0
	v_cvt_pk_bf16_f32 v172, v128, v163
	v_mul_f32_e32 v128, 0xbfb8aa3b, v28
	v_exp_f32_e32 v128, v128
	v_cvt_pk_bf16_f32 v173, v165, v169
	global_store_dwordx2 v[170:171], v[172:173], off offset:288
	v_add_u32_e32 v170, 0xa0, v168
	v_add_f32_e32 v128, 1.0, v128
	v_ashrrev_i32_e32 v171, 31, v170
	v_lshlrev_b64 v[170:171], 11, v[170:171]
	v_lshl_add_u64 v[170:171], v[166:167], 0, v[170:171]
	v_rcp_f32_e32 v128, v128
	s_nop 0
	v_mul_f32_e32 v163, 0xbfb8aa3b, v29
	v_exp_f32_e32 v163, v163
	v_add_u32_e32 v168, 0xb0, v168
	v_add_f32_e32 v163, 1.0, v163
	v_rcp_f32_e32 v163, v163
	s_nop 0
	v_mul_f32_e32 v165, 0xbfb8aa3b, v30
	v_exp_f32_e32 v165, v165
	s_nop 0
	v_add_f32_e32 v165, 1.0, v165
	v_rcp_f32_e32 v165, v165
	s_nop 0
	v_mul_f32_e32 v169, 0xbfb8aa3b, v31
	v_exp_f32_e32 v169, v169
	s_nop 0
	v_add_f32_e32 v169, 1.0, v169
	v_rcp_f32_e32 v169, v169
	s_nop 0
	v_cvt_pk_bf16_f32 v172, v128, v163
	v_mul_f32_e32 v128, 0xbfb8aa3b, v24
	v_exp_f32_e32 v128, v128
	v_cvt_pk_bf16_f32 v173, v165, v169
	global_store_dwordx2 v[170:171], v[172:173], off
	v_add_f32_e32 v128, 1.0, v128
	v_rcp_f32_e32 v128, v128
	s_nop 0
	v_mul_f32_e32 v163, 0xbfb8aa3b, v25
	v_exp_f32_e32 v163, v163
	s_nop 0
	v_add_f32_e32 v163, 1.0, v163
	v_rcp_f32_e32 v163, v163
	s_nop 0
	v_mul_f32_e32 v165, 0xbfb8aa3b, v26
	v_exp_f32_e32 v165, v165
	s_nop 0
	v_add_f32_e32 v165, 1.0, v165
	v_rcp_f32_e32 v165, v165
	s_nop 0
	v_mul_f32_e32 v169, 0xbfb8aa3b, v27
	v_exp_f32_e32 v169, v169
	s_nop 0
	v_add_f32_e32 v169, 1.0, v169
	v_rcp_f32_e32 v169, v169
	s_nop 0
	v_cvt_pk_bf16_f32 v172, v128, v163
	v_mul_f32_e32 v128, 0xbfb8aa3b, v20
	v_exp_f32_e32 v128, v128
	v_cvt_pk_bf16_f32 v173, v165, v169
	global_store_dwordx2 v[170:171], v[172:173], off offset:32
	v_add_f32_e32 v128, 1.0, v128
	v_rcp_f32_e32 v128, v128
	s_nop 0
	v_mul_f32_e32 v163, 0xbfb8aa3b, v21
	v_exp_f32_e32 v163, v163
	s_nop 0
	v_add_f32_e32 v163, 1.0, v163
	v_rcp_f32_e32 v163, v163
	s_nop 0
	v_mul_f32_e32 v165, 0xbfb8aa3b, v22
	v_exp_f32_e32 v165, v165
	s_nop 0
	v_add_f32_e32 v165, 1.0, v165
	v_rcp_f32_e32 v165, v165
	s_nop 0
	v_mul_f32_e32 v169, 0xbfb8aa3b, v23
	v_exp_f32_e32 v169, v169
	s_nop 0
	v_add_f32_e32 v169, 1.0, v169
	v_rcp_f32_e32 v169, v169
	s_nop 0
	v_cvt_pk_bf16_f32 v172, v128, v163
	v_mul_f32_e32 v128, 0xbfb8aa3b, v16
	v_exp_f32_e32 v128, v128
	v_cvt_pk_bf16_f32 v173, v165, v169
	global_store_dwordx2 v[170:171], v[172:173], off offset:256
	v_add_f32_e32 v128, 1.0, v128
	v_rcp_f32_e32 v128, v128
	s_nop 0
	v_mul_f32_e32 v163, 0xbfb8aa3b, v17
	v_exp_f32_e32 v163, v163
	s_nop 0
	v_add_f32_e32 v163, 1.0, v163
	v_rcp_f32_e32 v163, v163
	s_nop 0
	v_mul_f32_e32 v165, 0xbfb8aa3b, v18
	v_exp_f32_e32 v165, v165
	s_nop 0
	v_add_f32_e32 v165, 1.0, v165
	v_rcp_f32_e32 v165, v165
	s_nop 0
	v_mul_f32_e32 v169, 0xbfb8aa3b, v19
	v_exp_f32_e32 v169, v169
	s_nop 0
	v_add_f32_e32 v169, 1.0, v169
	v_rcp_f32_e32 v169, v169
	s_nop 0
	v_cvt_pk_bf16_f32 v172, v128, v163
	v_mul_f32_e32 v128, 0xbfb8aa3b, v12
	v_exp_f32_e32 v128, v128
	v_cvt_pk_bf16_f32 v173, v165, v169
	v_ashrrev_i32_e32 v169, 31, v168
	v_lshlrev_b64 v[168:169], 11, v[168:169]
	v_add_f32_e32 v128, 1.0, v128
	v_lshl_add_u64 v[166:167], v[166:167], 0, v[168:169]
	global_store_dwordx2 v[170:171], v[172:173], off offset:288
	v_rcp_f32_e32 v128, v128
	s_nop 0
	v_mul_f32_e32 v163, 0xbfb8aa3b, v13
	v_exp_f32_e32 v163, v163
	s_nop 0
	v_add_f32_e32 v163, 1.0, v163
	v_rcp_f32_e32 v163, v163
	s_nop 0
	v_mul_f32_e32 v165, 0xbfb8aa3b, v14
	v_exp_f32_e32 v165, v165
	s_nop 0
	v_add_f32_e32 v165, 1.0, v165
	v_rcp_f32_e32 v165, v165
	s_nop 0
	v_mul_f32_e32 v168, 0xbfb8aa3b, v15
	v_exp_f32_e32 v168, v168
	s_nop 0
	v_add_f32_e32 v168, 1.0, v168
	v_rcp_f32_e32 v169, v168
	s_nop 0
	v_cvt_pk_bf16_f32 v168, v128, v163
	v_mul_f32_e32 v128, 0xbfb8aa3b, v8
	v_exp_f32_e32 v128, v128
	v_cvt_pk_bf16_f32 v169, v165, v169
	global_store_dwordx2 v[166:167], v[168:169], off
	v_add_f32_e32 v128, 1.0, v128
	v_rcp_f32_e32 v128, v128
	s_nop 0
	v_mul_f32_e32 v163, 0xbfb8aa3b, v9
	v_exp_f32_e32 v163, v163
	s_nop 0
	v_add_f32_e32 v163, 1.0, v163
	v_rcp_f32_e32 v163, v163
	s_nop 0
	v_mul_f32_e32 v165, 0xbfb8aa3b, v10
	v_exp_f32_e32 v165, v165
	s_nop 0
	v_add_f32_e32 v165, 1.0, v165
	v_rcp_f32_e32 v165, v165
	s_nop 0
	v_mul_f32_e32 v168, 0xbfb8aa3b, v11
	v_exp_f32_e32 v168, v168
	s_nop 0
	v_add_f32_e32 v168, 1.0, v168
	v_rcp_f32_e32 v169, v168
	s_nop 0
	v_cvt_pk_bf16_f32 v168, v128, v163
	v_mul_f32_e32 v128, 0xbfb8aa3b, v4
	v_exp_f32_e32 v128, v128
	v_cvt_pk_bf16_f32 v169, v165, v169
	global_store_dwordx2 v[166:167], v[168:169], off offset:32
	v_add_f32_e32 v128, 1.0, v128
	v_rcp_f32_e32 v128, v128
	s_nop 0
	v_mul_f32_e32 v163, 0xbfb8aa3b, v5
	v_exp_f32_e32 v163, v163
	s_nop 0
	v_add_f32_e32 v163, 1.0, v163
	v_rcp_f32_e32 v163, v163
	s_nop 0
	v_mul_f32_e32 v165, 0xbfb8aa3b, v6
	v_exp_f32_e32 v165, v165
	s_nop 0
	v_add_f32_e32 v165, 1.0, v165
	v_rcp_f32_e32 v165, v165
	s_nop 0
	v_mul_f32_e32 v168, 0xbfb8aa3b, v7
	v_exp_f32_e32 v168, v168
	s_nop 0
	v_add_f32_e32 v168, 1.0, v168
	v_rcp_f32_e32 v169, v168
	s_nop 0
	v_cvt_pk_bf16_f32 v168, v128, v163
	v_mul_f32_e32 v128, 0xbfb8aa3b, v0
	v_exp_f32_e32 v128, v128
	v_cvt_pk_bf16_f32 v169, v165, v169
	global_store_dwordx2 v[166:167], v[168:169], off offset:256
	v_add_f32_e32 v128, 1.0, v128
	v_rcp_f32_e32 v128, v128
	s_nop 0
	v_mul_f32_e32 v163, 0xbfb8aa3b, v1
	v_exp_f32_e32 v163, v163
	s_nop 0
	v_add_f32_e32 v163, 1.0, v163
	v_rcp_f32_e32 v163, v163
	s_nop 0
	v_mul_f32_e32 v165, 0xbfb8aa3b, v2
	v_exp_f32_e32 v165, v165
	s_nop 0
	v_add_f32_e32 v165, 1.0, v165
	v_rcp_f32_e32 v165, v165
	s_nop 0
	v_mul_f32_e32 v168, 0xbfb8aa3b, v3
	v_exp_f32_e32 v168, v168
	s_nop 0
	v_add_f32_e32 v168, 1.0, v168
	v_rcp_f32_e32 v169, v168
	s_nop 0
	v_cvt_pk_bf16_f32 v168, v128, v163
	v_cvt_pk_bf16_f32 v169, v165, v169
	global_store_dwordx2 v[166:167], v[168:169], off offset:288

; __device__ __forceinline__ u32x2 pk4(f32x4 v) { u32x2 w; w.x = pk2(v[0], v[1]); w.y = pk2(v[2], v[3]); return w; }
; __device__ __forceinline__ f32x4 ldbf4(const bf16_t* p) { const u32x2 w = *(const u32x2*)p; f32x4 v; v[0] = __uint_as_float(w.x << 16); v[1] = __uint_as_float(w.x & 0xffff0000u); v[2] = __uint_as_float(w.y << 16); v[3] = __uint_as_float(w.y & 0xffff0000u); return v; }
; __device__ __forceinline__ void phase_mlaprep(KP p, int l, int gw, int NGW, int lane) {
;     unsigned char* ws = p->ws; const float* ZR = (const float*)(ws + W_ZR); bf16_t* CQN = (bf16_t*)(ws + W_CQN); bf16_t* CKVA = (bf16_t*)(ws + W_CKVA); bf16_t* KM = (bf16_t*)(ws + W_KM);
;     const float* RT = (const float*)(ws + W_RT);
;     const float* gq = p->in[13] + l * 768; const float* gkv = p->in[15] + l * 256;
;     float* ckp = p->out + O_CKP + (size_t)l * 8 * 4112 * 256; float* cks = p->out + O_CKS + (size_t)l * 128 * 256;
;     float* krp = p->out + O_KRP + (size_t)l * 8 * 4112 * 32; float* krs = p->out + O_KRS + (size_t)l * 128 * 32;
;     for (int r = gw; r < RM1; r += NGW) {
;         const float* z = ZR + (size_t)r * ZRW;
;         { f32x4 v[3]; float ss = 0.f; bf16_t* cq = CQN + (size_t)r * 768;
; #pragma unroll
;           for (int j = 0; j < 3; ++j) { v[j] = ldbf4(cq + (lane + 64 * j) * 4); ss += (v[j][0] * v[j][0] + v[j][1] * v[j][1]) + (v[j][2] * v[j][2] + v[j][3] * v[j][3]); }
;           const float rstd = 1.0f / sqrtf(wave_sum(ss, lane) * (1.f / 768.f) + EPS);
; #pragma unroll
;           for (int j = 0; j < 3; ++j) ((u32x2*)cq)[lane + 64 * j] = pk4(v[j] * rstd * ((const f32x4*)gq)[lane + 64 * j]); }
;         { f32x4 v = ((const f32x4*)(z + 768))[lane]; const float ss = (v[0] * v[0] + v[1] * v[1]) + (v[2] * v[2] + v[3] * v[3]);
;           const float rstd = 1.0f / sqrtf(wave_sum(ss, lane) * (1.f / 256.f) + EPS);
;           v = v * rstd * ((const f32x4*)gkv)[lane];
.LBB0_283:
	s_or_b64 exec, exec, s[0:1]
	s_mov_b64 s[18:19], s[80:81]
	v_mov_b32_e32 v5, v194
	s_mov_b32 s0, s79
	s_waitcnt lgkmcnt(0)
	s_barrier
	s_load_dwordx4 s[40:43], s[18:19], 0xd0
	v_readfirstlane_b32 s1, v5
	s_ashr_i32 s16, s1, 6
	s_lshl_b32 s17, s0, 3
	s_add_i32 s0, s17, s16
	s_waitcnt lgkmcnt(0)
	s_add_u32 s28, s42, 0x36d28000
	s_addc_u32 s29, s43, 0
	s_add_u32 s26, s42, 0x3b1a8000
	s_addc_u32 s27, s43, 0
	s_cmp_gt_i32 s0, 0x808f
	v_and_b32_e32 v4, 63, v5
	s_cbranch_scc1 .LBB0_322
	s_add_u32 s1, s42, 0x2b7c0000
	s_addc_u32 s15, s43, 0
	s_add_u32 s35, s42, 0x33cc8000
	v_readlane_b32 s38, v255, 26
	s_addc_u32 s44, s43, 0
	s_mul_i32 s22, s38, 0x404000
	s_mul_hi_u32 s20, s38, 0x404000
	s_add_u32 s22, s40, s22
	s_addc_u32 s20, s41, s20
	v_readlane_b32 s39, v255, 27
	s_add_u32 s45, s22, 0x50980000
	s_addc_u32 s46, s20, 0
	s_lshl_b64 s[22:23], s[38:39], 14
	s_add_u32 s20, s40, s22
	s_addc_u32 s24, s41, s23
	s_load_dwordx2 s[22:23], s[18:19], 0x68
	s_load_dwordx2 s[30:31], s[18:19], 0x78
	s_add_u32 s47, s20, 0x51990000
	s_mul_i32 s20, s38, 0x300
	s_addc_u32 s54, s24, 0
	s_lshl_b64 s[24:25], s[20:21], 2
	s_waitcnt lgkmcnt(0)
	s_add_u32 s48, s22, s24
	s_addc_u32 s49, s23, s25
	s_lshl_b64 s[22:23], s[38:39], 17
	s_add_u32 s20, s40, s22
	s_addc_u32 s23, s41, s23
	s_add_u32 s22, s20, 0x50900000
	s_addc_u32 s23, s23, 0
	s_mul_i32 s24, s38, 0x2020000
	s_mul_hi_u32 s20, s38, 0x2020000
	s_add_u32 s24, s40, s24
	s_addc_u32 s20, s41, s20
	s_add_u32 s24, s24, 0x48880000
	s_addc_u32 s25, s20, 0
	s_lshl_b32 s20, s38, 8
	s_lshl_b64 s[38:39], s[20:21], 2
	s_add_u32 s30, s30, s38
	v_lshlrev_b32_e32 v2, 3, v4
	v_mov_b32_e32 v3, v129
	v_and_b32_e32 v10, 15, v5
	s_addc_u32 s31, s31, s39
	v_lshlrev_b32_e32 v128, 4, v4
	v_lshl_add_u64 v[8:9], s[28:29], 0, v[2:3]
	v_lshlrev_b32_e32 v2, 3, v10
	v_lshl_add_u64 v[6:7], s[30:31], 0, v[128:129]
	v_lshl_add_u64 v[2:3], s[42:43], 0, v[2:3]
	s_mov_b64 s[30:31], 0x74ff1900
	v_lshl_add_u64 v[12:13], v[2:3], 0, s[30:31]
	v_lshrrev_b32_e32 v1, 4, v4
	v_readlane_b32 s30, v254, 58
	v_mul_u32_u24_e32 v1, 0x60, v1
	v_lshlrev_b32_e32 v2, 1, v10
	v_mov_b32_e32 v3, v129
	v_readlane_b32 s31, v254, 59
	s_add_u32 s30, s40, s30
	v_lshlrev_b32_e32 v0, 2, v4
	v_lshl_add_u64 v[2:3], s[26:27], 0, v[2:3]
	v_lshlrev_b32_e32 v16, 1, v1
	v_mov_b32_e32 v17, v129
	s_addc_u32 s31, s41, s31
	s_add_i32 s16, s17, s16
	v_xor_b32_e32 v11, 4, v0
	v_xor_b32_e32 v22, 8, v0
	v_xor_b32_e32 v23, 16, v0
	v_xor_b32_e32 v24, 32, v0
	v_xor_b32_e32 v25, 64, v0
	v_xor_b32_e32 v26, 0x80, v0
	v_cmp_gt_u32_e64 s[38:39], 16, v4
	v_lshl_add_u64 v[14:15], s[48:49], 0, v[128:129]
	v_lshl_add_u64 v[16:17], v[2:3], 0, v[16:17]
	v_lshl_add_u64 v[18:19], s[30:31], 0, v[128:129]
	s_add_i32 s30, s16, 0xffff7f80
	v_lshlrev_b32_e32 v27, 1, v0
	s_mov_b32 s42, s0
	global_load_dwordx4 v[72:75], v[14:15], off
	global_load_dwordx4 v[76:79], v[14:15], off offset:1024
	global_load_dwordx4 v[80:83], v[14:15], off offset:2048
	global_load_dwordx4 v[84:87], v[6:7], off
	v_lshlrev_b32_e32 v94, 2, v10
	v_add_u32_e32 v94, 0x1000, v94
	s_branch .LBB0_287

; __device__ __forceinline__ u32x2 pk4(f32x4 v) { u32x2 w; w.x = pk2(v[0], v[1]); w.y = pk2(v[2], v[3]); return w; }
; __device__ __forceinline__ f32x4 ldbf4(const bf16_t* p) { const u32x2 w = *(const u32x2*)p; f32x4 v; v[0] = __uint_as_float(w.x << 16); v[1] = __uint_as_float(w.x & 0xffff0000u); v[2] = __uint_as_float(w.y << 16); v[3] = __uint_as_float(w.y & 0xffff0000u); return v; }
; __device__ __forceinline__ void phase_mlaprep(KP p, int l, int gw, int NGW, int lane) {
;     ...
;     for (int r = gw; r < RM1; r += NGW) {
;         const float* z = ZR + (size_t)r * ZRW;
;         { f32x4 v[3]; float ss = 0.f; bf16_t* cq = CQN + (size_t)r * 768;
; #pragma unroll
;           for (int j = 0; j < 3; ++j) { v[j] = ldbf4(cq + (lane + 64 * j) * 4); ss += (v[j][0] * v[j][0] + v[j][1] * v[j][1]) + (v[j][2] * v[j][2] + v[j][3] * v[j][3]); }
;           const float rstd = 1.0f / sqrtf(wave_sum(ss, lane) * (1.f / 768.f) + EPS);
; #pragma unroll
;           for (int j = 0; j < 3; ++j) ((u32x2*)cq)[lane + 64 * j] = pk4(v[j] * rstd * ((const f32x4*)gq)[lane + 64 * j]); }
;         { f32x4 v = ((const f32x4*)(z + 768))[lane]; const float ss = (v[0] * v[0] + v[1] * v[1]) + (v[2] * v[2] + v[3] * v[3]);
;           const float rstd = 1.0f / sqrtf(wave_sum(ss, lane) * (1.f / 256.f) + EPS);
;           v = v * rstd * ((const f32x4*)gkv)[lane];
;           ((u32x2*)(CKVA + (size_t)r * 256))[lane] = pk4(v);
;           if (r < RP) { const int b = r >> 12, t = r & 4095; ((f32x4*)(ckp + (size_t)(b * 4112 + 16 + t) * 256))[lane] = v; }
.LBB0_287:
	s_ashr_i32 s43, s42, 31
	s_mul_i32 s16, s42, 0x600
	s_mul_hi_i32 s17, s42, 0x600
	s_add_u32 s16, s35, s16
	s_addc_u32 s17, s44, s17
	global_load_dwordx2 v[20:21], v27, s[16:17]
	global_load_dwordx2 v[28:29], v27, s[16:17] offset:512
	global_load_dwordx2 v[30:31], v27, s[16:17] offset:1024
	s_mul_i32 s31, s42, 0x1080
	s_mul_hi_i32 s20, s42, 0x1080
	s_add_u32 s48, s1, s31
	v_lshlrev_b32_e32 v128, 4, v4
	s_addc_u32 s49, s15, s20
	global_load_dwordx4 v[88:91], v128, s[48:49] offset:3072
	global_load_dword v92, v94, s[48:49]
	global_load_dword v93, v94, s[48:49] offset:64
	s_waitcnt vmcnt(5)
	v_lshlrev_b32_e32 v32, 16, v20
	v_and_b32_e32 v33, 0xffff0000, v20
	v_lshlrev_b32_e32 v20, 16, v21
	v_and_b32_e32 v21, 0xffff0000, v21
	s_waitcnt vmcnt(4)
	v_lshlrev_b32_e32 v34, 16, v28
	v_and_b32_e32 v35, 0xffff0000, v28
	v_lshlrev_b32_e32 v28, 16, v29
	v_and_b32_e32 v29, 0xffff0000, v29
	s_waitcnt vmcnt(3)
	v_lshlrev_b32_e32 v37, 16, v30
	v_and_b32_e32 v39, 0xffff0000, v30
	v_lshlrev_b32_e32 v30, 16, v31
	v_and_b32_e32 v31, 0xffff0000, v31
	v_mul_f32_e32 v36, v32, v32
	v_mul_f32_e32 v40, v33, v33
	v_mov_b32_e32 v41, v37
	v_mul_f32_e32 v38, v21, v21
	v_mul_f32_e32 v42, v35, v35
	v_mul_f32_e32 v44, v29, v29
	v_mul_f32_e32 v50, v39, v39
	v_mul_f32_e32 v51, v30, v30
	v_mul_f32_e32 v52, v31, v31
	v_pk_add_f32 v[40:41], v[36:37], v[40:41]
	v_pk_mul_f32 v[46:47], v[36:37], v[36:37]
	v_pk_fma_f32 v[48:49], v[20:21], v[20:21], v[38:39] op_sel_hi:[1,1,0]
	v_pk_fma_f32 v[42:43], v[34:35], v[34:35], v[42:43] op_sel_hi:[1,1,0]
	v_pk_fma_f32 v[44:45], v[28:29], v[28:29], v[44:45] op_sel_hi:[1,1,0]
	v_mov_b32_e32 v41, v47
	v_mov_b32_e32 v49, v50
	v_mov_b32_e32 v43, v51
	v_mov_b32_e32 v45, v52
	v_pk_add_f32 v[40:41], v[40:41], v[48:49]
	v_pk_add_f32 v[42:43], v[42:43], v[44:45]
	s_nop 0
	v_pk_add_f32 v[40:41], v[40:41], v[42:43]
	s_nop 0
	v_add_f32_e32 v36, v40, v41
	ds_bpermute_b32 v38, v11, v36
	s_waitcnt lgkmcnt(0)
	v_add_f32_e32 v36, v36, v38
	ds_bpermute_b32 v38, v22, v36
	s_waitcnt lgkmcnt(0)
	v_add_f32_e32 v36, v36, v38
	ds_bpermute_b32 v38, v23, v36
	s_waitcnt lgkmcnt(0)
	v_add_f32_e32 v36, v36, v38
	ds_bpermute_b32 v38, v24, v36
	s_waitcnt lgkmcnt(0)
	v_add_f32_e32 v36, v36, v38
	ds_bpermute_b32 v38, v25, v36
	s_waitcnt lgkmcnt(0)
	v_add_f32_e32 v36, v36, v38
	ds_bpermute_b32 v38, v26, v36
	s_waitcnt lgkmcnt(0)
	v_add_f32_e32 v36, v36, v38
	v_fmamk_f32 v36, v36, 0x3aaaaaab, v195
	v_mul_f32_e32 v38, 0x4f800000, v36
	v_cmp_gt_f32_e32 vcc, s89, v36
	s_nop 1
	v_cndmask_b32_e32 v36, v36, v38, vcc
	v_sqrt_f32_e32 v38, v36
	s_nop 0
	v_add_u32_e32 v40, -1, v38
	v_add_u32_e32 v41, 1, v38
	v_fma_f32 v42, -v40, v38, v36
	v_fma_f32 v43, -v41, v38, v36
	v_cmp_ge_f32_e64 s[40:41], 0, v42
	s_nop 1
	v_cndmask_b32_e64 v38, v38, v40, s[40:41]
	v_cmp_lt_f32_e64 s[40:41], 0, v43
	s_nop 1
	v_cndmask_b32_e64 v38, v38, v41, s[40:41]
	v_mul_f32_e32 v40, 0x37800000, v38
	v_cndmask_b32_e32 v38, v38, v40, vcc
	v_cmp_class_f32_e32 vcc, v36, v196
	v_lshlrev_b32_e32 v41, 3, v4
	s_nop 0
	v_cndmask_b32_e32 v36, v38, v36, vcc
	v_div_scale_f32 v38, s[40:41], v36, v36, 1.0
	v_rcp_f32_e32 v40, v38
	v_div_scale_f32 v42, vcc, 1.0, v36, 1.0
	v_fma_f32 v43, -v38, v40, 1.0
	v_fmac_f32_e32 v40, v43, v40
	v_mul_f32_e32 v43, v42, v40
	v_fma_f32 v44, -v38, v43, v42
	v_fmac_f32_e32 v43, v44, v40
	v_fma_f32 v38, -v38, v43, v42
	v_div_fmas_f32 v38, v38, v40, v43
	v_div_fixup_f32 v36, v38, v36, 1.0
	v_pk_mul_f32 v[32:33], v[32:33], v[36:37] op_sel_hi:[1,0]
	v_pk_mul_f32 v[20:21], v[20:21], v[36:37] op_sel_hi:[1,0]
	v_pk_mul_f32 v[0:1], v[72:73], v[32:33]
	v_pk_mul_f32 v[2:3], v[74:75], v[20:21]
	v_cvt_pk_bf16_f32 v0, v0, v1
	v_pk_mul_f32 v[20:21], v[36:37], v[34:35] op_sel_hi:[0,1]
	v_cvt_pk_bf16_f32 v1, v2, v3
	global_store_dwordx2 v41, v[0:1], s[16:17]
	v_pk_mul_f32 v[28:29], v[36:37], v[28:29] op_sel_hi:[0,1]
	v_mov_b32_e32 v38, v37
	v_pk_mul_f32 v[0:1], v[76:77], v[20:21]
	v_pk_mul_f32 v[2:3], v[78:79], v[28:29]
	v_cvt_pk_bf16_f32 v0, v0, v1
	v_pk_mul_f32 v[20:21], v[38:39], v[36:37] op_sel_hi:[1,0]
	v_cvt_pk_bf16_f32 v1, v2, v3
	global_store_dwordx2 v41, v[0:1], s[16:17] offset:512
	v_pk_mul_f32 v[28:29], v[30:31], v[36:37] op_sel_hi:[1,0]
	v_pk_mul_f32 v[0:1], v[80:81], v[20:21]
	v_pk_mul_f32 v[2:3], v[82:83], v[28:29]
	v_cvt_pk_bf16_f32 v0, v0, v1
	s_nop 0
	v_cvt_pk_bf16_f32 v1, v2, v3
	global_store_dwordx2 v41, v[0:1], s[16:17] offset:1024
	s_waitcnt vmcnt(0)
	v_mov_b32_e32 v0, v88
	v_mov_b32_e32 v1, v89
	v_mov_b32_e32 v2, v90
	v_mov_b32_e32 v3, v91
	s_lshl_b64 s[16:17], s[42:43], 9
	s_cmpk_gt_i32 s42, 0x7fff
	v_pk_mul_f32 v[20:21], v[2:3], v[2:3]
	v_pk_mul_f32 v[32:33], v[0:1], v[0:1]
	s_nop 0
	v_pk_mov_b32 v[34:35], v[32:33], v[20:21] op_sel:[1,0]
	v_mov_b32_e32 v33, v21
	v_pk_add_f32 v[20:21], v[34:35], v[32:33]
	s_nop 0
	v_add_f32_e32 v20, v20, v21
	ds_bpermute_b32 v21, v11, v20
	s_waitcnt lgkmcnt(0)
	v_add_f32_e32 v20, v20, v21
	ds_bpermute_b32 v21, v22, v20
	s_waitcnt lgkmcnt(0)
	v_add_f32_e32 v20, v20, v21
	ds_bpermute_b32 v21, v23, v20
	s_waitcnt lgkmcnt(0)
	v_add_f32_e32 v20, v20, v21
	ds_bpermute_b32 v21, v24, v20
	s_waitcnt lgkmcnt(0)
	v_add_f32_e32 v20, v20, v21
	ds_bpermute_b32 v21, v25, v20
	s_waitcnt lgkmcnt(0)
	v_add_f32_e32 v20, v20, v21
	ds_bpermute_b32 v21, v26, v20
	s_waitcnt lgkmcnt(0)
	v_add_f32_e32 v20, v20, v21
	v_fmamk_f32 v20, v20, 0x3b800000, v195
	v_mul_f32_e32 v21, 0x4f800000, v20
	v_cmp_gt_f32_e32 vcc, s89, v20
	s_nop 1
	v_cndmask_b32_e32 v32, v20, v21, vcc
	v_sqrt_f32_e32 v33, v32
	v_lshl_add_u64 v[20:21], v[8:9], 0, s[16:17]
	s_cselect_b64 s[16:17], -1, 0
	v_add_u32_e32 v34, -1, v33
	v_add_u32_e32 v35, 1, v33
	v_fma_f32 v36, -v34, v33, v32
	v_fma_f32 v37, -v35, v33, v32
	v_cmp_ge_f32_e64 s[40:41], 0, v36
	s_nop 1
	v_cndmask_b32_e64 v33, v33, v34, s[40:41]
	v_cmp_lt_f32_e64 s[40:41], 0, v37
	s_nop 1
	v_cndmask_b32_e64 v33, v33, v35, s[40:41]
	v_mul_f32_e32 v34, 0x37800000, v33
	v_cndmask_b32_e32 v33, v33, v34, vcc
	v_cmp_class_f32_e32 vcc, v32, v196
	s_nop 1
	v_cndmask_b32_e32 v32, v33, v32, vcc
	v_div_scale_f32 v33, s[40:41], v32, v32, 1.0
	v_rcp_f32_e32 v34, v33
	v_div_scale_f32 v35, vcc, 1.0, v32, 1.0
	s_and_b64 s[40:41], exec, s[16:17]
	v_fma_f32 v36, -v33, v34, 1.0
	v_fmac_f32_e32 v34, v36, v34
	v_mul_f32_e32 v36, v35, v34
	v_fma_f32 v37, -v33, v36, v35
	v_fmac_f32_e32 v36, v37, v34
	v_fma_f32 v33, -v33, v36, v35
	v_div_fmas_f32 v33, v33, v34, v36
	v_div_fixup_f32 v32, v33, v32, 1.0
	v_pk_mul_f32 v[0:1], v[0:1], v[32:33] op_sel_hi:[1,0]
	v_pk_mul_f32 v[2:3], v[2:3], v[32:33] op_sel_hi:[1,0]
	v_pk_mul_f32 v[0:1], v[84:85], v[0:1]
	v_pk_mul_f32 v[2:3], v[86:87], v[2:3]
	s_mov_b64 vcc, s[40:41]
	v_cvt_pk_bf16_f32 v28, v0, v1
	v_cvt_pk_bf16_f32 v29, v2, v3
	global_store_dwordx2 v[20:21], v[28:29], off
	s_cbranch_vccz .LBB0_294
	s_cmpk_gt_u32 s42, 0x807f
	s_mov_b64 s[40:41], -1
	s_cbranch_scc0 .LBB0_292
	s_mov_b32 s31, s21
	s_lshl_b64 s[40:41], s[30:31], 10
	v_lshl_add_u64 v[20:21], v[18:19], 0, s[40:41]
	s_mov_b64 s[40:41], 0

; __device__ __forceinline__ unsigned pk2(float lo, float hi) { return pg8::cvt_pk_bf16(lo, hi); }
; __device__ __forceinline__ void phase_mlaprep(KP p, int l, int gw, int NGW, int lane) {
;     ...
;         { const int i = lane & 15; const float x1 = z[1024 + i], x2 = z[1040 + i]; const int pos = row_pos(r);
;           const float c = RT[((size_t)(pos + 16) * 16 + i) * 2], s = RT[((size_t)(pos + 16) * 16 + i) * 2 + 1];
;           const float o1 = x1 * c - x2 * s, o2 = x1 * s + x2 * c;
;           const unsigned pk = pk2(o1, o2); const unsigned short b1 = (unsigned short)(pk & 0xffffu), b2 = (unsigned short)(pk >> 16);
.LBB0_299:
	v_lshlrev_b32_e32 v128, 2, v10
	s_nop 0
	v_lshl_add_u64 v[0:1], s[48:49], 0, v[128:129]
	v_add_co_u32_e32 v2, vcc, 0x1000, v0
	v_readlane_b32 s50, v255, 8
	s_nop 0
	v_addc_co_u32_e32 v3, vcc, 0, v1, vcc
	v_mov_b32_e32 v0, v92
	v_mov_b32_e32 v3, v93
	s_mov_b64 s[40:41], -1
	s_and_b64 vcc, exec, s[16:17]
	v_readlane_b32 s51, v255, 9
	s_cbranch_vccz .LBB0_305
	s_cmpk_gt_u32 s42, 0x807f
	s_cbranch_scc0 .LBB0_302
	s_add_i32 s20, s42, 0xffff7f70
	s_mov_b64 s[40:41], 0

; __device__ __forceinline__ u32x2 pk4(f32x4 v) { u32x2 w; w.x = pk2(v[0], v[1]); w.y = pk2(v[2], v[3]); return w; }
; __device__ __forceinline__ f32x4 ldbf4(const bf16_t* p) { const u32x2 w = *(const u32x2*)p; f32x4 v; v[0] = __uint_as_float(w.x << 16); v[1] = __uint_as_float(w.x & 0xffff0000u); v[2] = __uint_as_float(w.y << 16); v[3] = __uint_as_float(w.y & 0xffff0000u); return v; }
;     __device__ __forceinline__ void operator()(const f32x4 (&acc)[2][2][4][2], const Unit& u, int wr, int wc, int fr, int fq) const {
;     ...
;         if (u.nt == ntf) {
; #pragma unroll
;             for (int ai = 0; ai < 2; ++ai)
; #pragma unroll
;                 for (int m = 0; m < 4; ++m) { bf16_t* rp = H + (size_t)(u.pm * 256 + ai * 128 + m * 16 + lr0) * 1024 + c0;
; #pragma unroll
;                     for (int bj = 0; bj < 2; ++bj)
; #pragma unroll
;                         for (int n = 0; n < 2; ++n) { bf16_t* q = rp + bj * 128 + n * 16; *(u32x2*)q = pk4(ldbf4(q) + acc[ai][bj][m][n]); } }
.LBB0_1093:
	s_lshl_b32 s16, s71, 8
	v_add_u32_e32 v140, s16, v132
	v_add_u32_e32 v141, s16, v133
	v_add_u32_e32 v143, s16, v145
	v_add_u32_e32 v149, s16, v146
	v_lshlrev_b32_e32 v150, 1, v142
	v_lshl_add_u32 v160, v140, 11, v150
	v_lshl_add_u32 v161, v141, 11, v150
	v_lshl_add_u32 v162, v143, 11, v150
	v_lshl_add_u32 v163, v149, 11, v150
	v_add_u32_e32 v164, 0x40000, v160
	v_add_u32_e32 v165, 0x48000, v160
	v_add_u32_e32 v166, 0x50000, v160
	v_add_u32_e32 v167, 0x58000, v160
	global_load_dwordx2 v[198:199], v160, s[40:41]
	global_load_dwordx2 v[200:201], v160, s[40:41] offset:32
	global_load_dwordx2 v[202:203], v160, s[40:41] offset:256
	global_load_dwordx2 v[204:205], v160, s[40:41] offset:288
	global_load_dwordx2 v[206:207], v161, s[40:41]
	global_load_dwordx2 v[208:209], v161, s[40:41] offset:32
	global_load_dwordx2 v[210:211], v161, s[40:41] offset:256
	global_load_dwordx2 v[212:213], v161, s[40:41] offset:288
	global_load_dwordx2 v[214:215], v162, s[40:41]
	global_load_dwordx2 v[216:217], v162, s[40:41] offset:32
	global_load_dwordx2 v[218:219], v162, s[40:41] offset:256
	global_load_dwordx2 v[220:221], v162, s[40:41] offset:288
	global_load_dwordx2 v[222:223], v163, s[40:41]
	global_load_dwordx2 v[224:225], v163, s[40:41] offset:32
	global_load_dwordx2 v[226:227], v163, s[40:41] offset:256
	global_load_dwordx2 v[228:229], v163, s[40:41] offset:288
	global_load_dwordx2 v[230:231], v164, s[40:41]
	global_load_dwordx2 v[232:233], v164, s[40:41] offset:32
	global_load_dwordx2 v[234:235], v164, s[40:41] offset:256
	global_load_dwordx2 v[236:237], v164, s[40:41] offset:288
	global_load_dwordx2 v[238:239], v165, s[40:41]
	global_load_dwordx2 v[240:241], v165, s[40:41] offset:32
	global_load_dwordx2 v[242:243], v165, s[40:41] offset:256
	global_load_dwordx2 v[244:245], v165, s[40:41] offset:288
	global_load_dwordx2 v[246:247], v166, s[40:41]
	global_load_dwordx2 v[248:249], v166, s[40:41] offset:32
	global_load_dwordx2 v[250:251], v166, s[40:41] offset:256
	global_load_dwordx2 v[252:253], v166, s[40:41] offset:288
	global_load_dwordx2 v[182:183], v167, s[40:41]
	global_load_dwordx2 v[184:185], v167, s[40:41] offset:32
	global_load_dwordx2 v[186:187], v167, s[40:41] offset:256
	global_load_dwordx2 v[190:191], v167, s[40:41] offset:288
	s_waitcnt vmcnt(0)
	v_lshlrev_b32_e32 v168, 16, v198
	v_and_b32_e32 v169, 0xffff0000, v198
	v_lshlrev_b32_e32 v170, 16, v199
	v_and_b32_e32 v171, 0xffff0000, v199
	v_pk_add_f32 v[126:127], v[126:127], v[170:171]
	v_pk_add_f32 v[124:125], v[124:125], v[168:169]
	s_nop 0
	v_cvt_pk_bf16_f32 v124, v124, v125
	v_cvt_pk_bf16_f32 v125, v126, v127
	global_store_dwordx2 v160, v[124:125], s[40:41]
	v_lshlrev_b32_e32 v172, 16, v200
	v_and_b32_e32 v173, 0xffff0000, v200
	v_lshlrev_b32_e32 v174, 16, v201
	v_and_b32_e32 v175, 0xffff0000, v201
	v_pk_add_f32 v[122:123], v[122:123], v[174:175]
	v_pk_add_f32 v[120:121], v[120:121], v[172:173]
	s_nop 0
	v_cvt_pk_bf16_f32 v120, v120, v121
	v_cvt_pk_bf16_f32 v121, v122, v123
	global_store_dwordx2 v160, v[120:121], s[40:41] offset:32
	v_lshlrev_b32_e32 v168, 16, v202
	v_and_b32_e32 v169, 0xffff0000, v202
	v_lshlrev_b32_e32 v170, 16, v203
	v_and_b32_e32 v171, 0xffff0000, v203
	v_pk_add_f32 v[118:119], v[118:119], v[170:171]
	v_pk_add_f32 v[116:117], v[116:117], v[168:169]
	s_nop 0
	v_cvt_pk_bf16_f32 v116, v116, v117
	v_cvt_pk_bf16_f32 v117, v118, v119
	global_store_dwordx2 v160, v[116:117], s[40:41] offset:256
	v_lshlrev_b32_e32 v172, 16, v204
	v_and_b32_e32 v173, 0xffff0000, v204
	v_lshlrev_b32_e32 v174, 16, v205
	v_and_b32_e32 v175, 0xffff0000, v205
	v_pk_add_f32 v[114:115], v[114:115], v[174:175]
	v_pk_add_f32 v[112:113], v[112:113], v[172:173]
	s_nop 0
	v_cvt_pk_bf16_f32 v112, v112, v113
	v_cvt_pk_bf16_f32 v113, v114, v115
	global_store_dwordx2 v160, v[112:113], s[40:41] offset:288
	v_lshlrev_b32_e32 v168, 16, v206
	v_and_b32_e32 v169, 0xffff0000, v206
	v_lshlrev_b32_e32 v170, 16, v207
	v_and_b32_e32 v171, 0xffff0000, v207
	v_pk_add_f32 v[110:111], v[110:111], v[170:171]
	v_pk_add_f32 v[108:109], v[108:109], v[168:169]
	s_nop 0
	v_cvt_pk_bf16_f32 v108, v108, v109
	v_cvt_pk_bf16_f32 v109, v110, v111
	global_store_dwordx2 v161, v[108:109], s[40:41]
	v_lshlrev_b32_e32 v172, 16, v208
	v_and_b32_e32 v173, 0xffff0000, v208
	v_lshlrev_b32_e32 v174, 16, v209
	v_and_b32_e32 v175, 0xffff0000, v209
	v_pk_add_f32 v[106:107], v[106:107], v[174:175]
	v_pk_add_f32 v[104:105], v[104:105], v[172:173]
	s_nop 0
	v_cvt_pk_bf16_f32 v104, v104, v105
	v_cvt_pk_bf16_f32 v105, v106, v107
	global_store_dwordx2 v161, v[104:105], s[40:41] offset:32
	v_lshlrev_b32_e32 v168, 16, v210
	v_and_b32_e32 v169, 0xffff0000, v210
	v_lshlrev_b32_e32 v170, 16, v211
	v_and_b32_e32 v171, 0xffff0000, v211
	v_pk_add_f32 v[102:103], v[102:103], v[170:171]
	v_pk_add_f32 v[100:101], v[100:101], v[168:169]
	s_nop 0
	v_cvt_pk_bf16_f32 v100, v100, v101
	v_cvt_pk_bf16_f32 v101, v102, v103
	global_store_dwordx2 v161, v[100:101], s[40:41] offset:256
	v_lshlrev_b32_e32 v172, 16, v212
	v_and_b32_e32 v173, 0xffff0000, v212
	v_lshlrev_b32_e32 v174, 16, v213
	v_and_b32_e32 v175, 0xffff0000, v213
	v_pk_add_f32 v[98:99], v[98:99], v[174:175]
	v_pk_add_f32 v[96:97], v[96:97], v[172:173]
	s_nop 0
	v_cvt_pk_bf16_f32 v96, v96, v97
	v_cvt_pk_bf16_f32 v97, v98, v99
	global_store_dwordx2 v161, v[96:97], s[40:41] offset:288
	v_lshlrev_b32_e32 v168, 16, v214
	v_and_b32_e32 v169, 0xffff0000, v214
	v_lshlrev_b32_e32 v170, 16, v215
	v_and_b32_e32 v171, 0xffff0000, v215
	v_pk_add_f32 v[94:95], v[94:95], v[170:171]
	v_pk_add_f32 v[92:93], v[92:93], v[168:169]
	s_nop 0
	v_cvt_pk_bf16_f32 v92, v92, v93
	v_cvt_pk_bf16_f32 v93, v94, v95
; __device__ __forceinline__ u32x2 pk4(f32x4 v) { u32x2 w; w.x = pk2(v[0], v[1]); w.y = pk2(v[2], v[3]); return w; }
; __device__ __forceinline__ f32x4 ldbf4(const bf16_t* p) { const u32x2 w = *(const u32x2*)p; f32x4 v; v[0] = __uint_as_float(w.x << 16); v[1] = __uint_as_float(w.x & 0xffff0000u); v[2] = __uint_as_float(w.y << 16); v[3] = __uint_as_float(w.y & 0xffff0000u); return v; }
;     __device__ __forceinline__ void operator()(const f32x4 (&acc)[2][2][4][2], const Unit& u, int wr, int wc, int fr, int fq) const {
;     ...
;         if (u.nt == ntf) {
; #pragma unroll
;             for (int ai = 0; ai < 2; ++ai)
; #pragma unroll
;                 for (int m = 0; m < 4; ++m) { bf16_t* rp = H + (size_t)(u.pm * 256 + ai * 128 + m * 16 + lr0) * 1024 + c0;
; #pragma unroll
;                     for (int bj = 0; bj < 2; ++bj)
; #pragma unroll
;                         for (int n = 0; n < 2; ++n) { bf16_t* q = rp + bj * 128 + n * 16; *(u32x2*)q = pk4(ldbf4(q) + acc[ai][bj][m][n]); } }
	global_store_dwordx2 v162, v[92:93], s[40:41]
	v_lshlrev_b32_e32 v172, 16, v216
	v_and_b32_e32 v173, 0xffff0000, v216
	v_lshlrev_b32_e32 v174, 16, v217
	v_and_b32_e32 v175, 0xffff0000, v217
	v_pk_add_f32 v[90:91], v[90:91], v[174:175]
	v_pk_add_f32 v[88:89], v[88:89], v[172:173]
	s_nop 0
	v_cvt_pk_bf16_f32 v88, v88, v89
	v_cvt_pk_bf16_f32 v89, v90, v91
	global_store_dwordx2 v162, v[88:89], s[40:41] offset:32
	v_lshlrev_b32_e32 v168, 16, v218
	v_and_b32_e32 v169, 0xffff0000, v218
	v_lshlrev_b32_e32 v170, 16, v219
	v_and_b32_e32 v171, 0xffff0000, v219
	v_pk_add_f32 v[86:87], v[86:87], v[170:171]
	v_pk_add_f32 v[84:85], v[84:85], v[168:169]
	s_nop 0
	v_cvt_pk_bf16_f32 v84, v84, v85
	v_cvt_pk_bf16_f32 v85, v86, v87
	global_store_dwordx2 v162, v[84:85], s[40:41] offset:256
	v_lshlrev_b32_e32 v172, 16, v220
	v_and_b32_e32 v173, 0xffff0000, v220
	v_lshlrev_b32_e32 v174, 16, v221
	v_and_b32_e32 v175, 0xffff0000, v221
	v_pk_add_f32 v[82:83], v[82:83], v[174:175]
	v_pk_add_f32 v[80:81], v[80:81], v[172:173]
	s_nop 0
	v_cvt_pk_bf16_f32 v80, v80, v81
	v_cvt_pk_bf16_f32 v81, v82, v83
	global_store_dwordx2 v162, v[80:81], s[40:41] offset:288
	v_lshlrev_b32_e32 v168, 16, v222
	v_and_b32_e32 v169, 0xffff0000, v222
	v_lshlrev_b32_e32 v170, 16, v223
	v_and_b32_e32 v171, 0xffff0000, v223
	v_pk_add_f32 v[78:79], v[78:79], v[170:171]
	v_pk_add_f32 v[76:77], v[76:77], v[168:169]
	s_nop 0
	v_cvt_pk_bf16_f32 v76, v76, v77
	v_cvt_pk_bf16_f32 v77, v78, v79
	global_store_dwordx2 v163, v[76:77], s[40:41]
	v_lshlrev_b32_e32 v172, 16, v224
	v_and_b32_e32 v173, 0xffff0000, v224
	v_lshlrev_b32_e32 v174, 16, v225
	v_and_b32_e32 v175, 0xffff0000, v225
	v_pk_add_f32 v[74:75], v[74:75], v[174:175]
	v_pk_add_f32 v[72:73], v[72:73], v[172:173]
	s_nop 0
	v_cvt_pk_bf16_f32 v72, v72, v73
	v_cvt_pk_bf16_f32 v73, v74, v75
	global_store_dwordx2 v163, v[72:73], s[40:41] offset:32
	v_lshlrev_b32_e32 v168, 16, v226
	v_and_b32_e32 v169, 0xffff0000, v226
	v_lshlrev_b32_e32 v170, 16, v227
	v_and_b32_e32 v171, 0xffff0000, v227
	v_pk_add_f32 v[70:71], v[70:71], v[170:171]
	v_pk_add_f32 v[68:69], v[68:69], v[168:169]
	s_nop 0
	v_cvt_pk_bf16_f32 v68, v68, v69
	v_cvt_pk_bf16_f32 v69, v70, v71
	global_store_dwordx2 v163, v[68:69], s[40:41] offset:256
	v_lshlrev_b32_e32 v172, 16, v228
	v_and_b32_e32 v173, 0xffff0000, v228
	v_lshlrev_b32_e32 v174, 16, v229
	v_and_b32_e32 v175, 0xffff0000, v229
	v_pk_add_f32 v[66:67], v[66:67], v[174:175]
	v_pk_add_f32 v[64:65], v[64:65], v[172:173]
	s_nop 0
	v_cvt_pk_bf16_f32 v64, v64, v65
	v_cvt_pk_bf16_f32 v65, v66, v67
	global_store_dwordx2 v163, v[64:65], s[40:41] offset:288
	v_lshlrev_b32_e32 v168, 16, v230
	v_and_b32_e32 v169, 0xffff0000, v230
	v_lshlrev_b32_e32 v170, 16, v231
	v_and_b32_e32 v171, 0xffff0000, v231
	v_pk_add_f32 v[62:63], v[62:63], v[170:171]
	v_pk_add_f32 v[60:61], v[60:61], v[168:169]
	s_nop 0
	v_cvt_pk_bf16_f32 v60, v60, v61
	v_cvt_pk_bf16_f32 v61, v62, v63
	global_store_dwordx2 v164, v[60:61], s[40:41]
	v_lshlrev_b32_e32 v172, 16, v232
	v_and_b32_e32 v173, 0xffff0000, v232
	v_lshlrev_b32_e32 v174, 16, v233
	v_and_b32_e32 v175, 0xffff0000, v233
	v_pk_add_f32 v[58:59], v[58:59], v[174:175]
	v_pk_add_f32 v[56:57], v[56:57], v[172:173]
	s_nop 0
	v_cvt_pk_bf16_f32 v56, v56, v57
	v_cvt_pk_bf16_f32 v57, v58, v59
	global_store_dwordx2 v164, v[56:57], s[40:41] offset:32
	v_lshlrev_b32_e32 v168, 16, v234
	v_and_b32_e32 v169, 0xffff0000, v234
	v_lshlrev_b32_e32 v170, 16, v235
	v_and_b32_e32 v171, 0xffff0000, v235
	v_pk_add_f32 v[54:55], v[54:55], v[170:171]
	v_pk_add_f32 v[52:53], v[52:53], v[168:169]
	s_nop 0
	v_cvt_pk_bf16_f32 v52, v52, v53
	v_cvt_pk_bf16_f32 v53, v54, v55
	global_store_dwordx2 v164, v[52:53], s[40:41] offset:256
	v_lshlrev_b32_e32 v172, 16, v236
	v_and_b32_e32 v173, 0xffff0000, v236
	v_lshlrev_b32_e32 v174, 16, v237
	v_and_b32_e32 v175, 0xffff0000, v237
	v_pk_add_f32 v[50:51], v[50:51], v[174:175]
	v_pk_add_f32 v[48:49], v[48:49], v[172:173]
	s_nop 0
	v_cvt_pk_bf16_f32 v48, v48, v49
	v_cvt_pk_bf16_f32 v49, v50, v51
	global_store_dwordx2 v164, v[48:49], s[40:41] offset:288
	v_lshlrev_b32_e32 v168, 16, v238
	v_and_b32_e32 v169, 0xffff0000, v238
	v_lshlrev_b32_e32 v170, 16, v239
	v_and_b32_e32 v171, 0xffff0000, v239
	v_pk_add_f32 v[46:47], v[46:47], v[170:171]
; __device__ __forceinline__ u32x2 pk4(f32x4 v) { u32x2 w; w.x = pk2(v[0], v[1]); w.y = pk2(v[2], v[3]); return w; }
; __device__ __forceinline__ f32x4 ldbf4(const bf16_t* p) { const u32x2 w = *(const u32x2*)p; f32x4 v; v[0] = __uint_as_float(w.x << 16); v[1] = __uint_as_float(w.x & 0xffff0000u); v[2] = __uint_as_float(w.y << 16); v[3] = __uint_as_float(w.y & 0xffff0000u); return v; }
;     __device__ __forceinline__ void operator()(const f32x4 (&acc)[2][2][4][2], const Unit& u, int wr, int wc, int fr, int fq) const {
;     ...
;         if (u.nt == ntf) {
; #pragma unroll
;             for (int ai = 0; ai < 2; ++ai)
; #pragma unroll
;                 for (int m = 0; m < 4; ++m) { bf16_t* rp = H + (size_t)(u.pm * 256 + ai * 128 + m * 16 + lr0) * 1024 + c0;
; #pragma unroll
;                     for (int bj = 0; bj < 2; ++bj)
; #pragma unroll
;                         for (int n = 0; n < 2; ++n) { bf16_t* q = rp + bj * 128 + n * 16; *(u32x2*)q = pk4(ldbf4(q) + acc[ai][bj][m][n]); } }
	v_pk_add_f32 v[44:45], v[44:45], v[168:169]
	s_nop 0
	v_cvt_pk_bf16_f32 v44, v44, v45
	v_cvt_pk_bf16_f32 v45, v46, v47
	global_store_dwordx2 v165, v[44:45], s[40:41]
	v_lshlrev_b32_e32 v172, 16, v240
	v_and_b32_e32 v173, 0xffff0000, v240
	v_lshlrev_b32_e32 v174, 16, v241
	v_and_b32_e32 v175, 0xffff0000, v241
	v_pk_add_f32 v[42:43], v[42:43], v[174:175]
	v_pk_add_f32 v[40:41], v[40:41], v[172:173]
	s_nop 0
	v_cvt_pk_bf16_f32 v40, v40, v41
	v_cvt_pk_bf16_f32 v41, v42, v43
	global_store_dwordx2 v165, v[40:41], s[40:41] offset:32
	v_lshlrev_b32_e32 v168, 16, v242
	v_and_b32_e32 v169, 0xffff0000, v242
	v_lshlrev_b32_e32 v170, 16, v243
	v_and_b32_e32 v171, 0xffff0000, v243
	v_pk_add_f32 v[38:39], v[38:39], v[170:171]
	v_pk_add_f32 v[36:37], v[36:37], v[168:169]
	s_nop 0
	v_cvt_pk_bf16_f32 v36, v36, v37
	v_cvt_pk_bf16_f32 v37, v38, v39
	global_store_dwordx2 v165, v[36:37], s[40:41] offset:256
	v_lshlrev_b32_e32 v172, 16, v244
	v_and_b32_e32 v173, 0xffff0000, v244
	v_lshlrev_b32_e32 v174, 16, v245
	v_and_b32_e32 v175, 0xffff0000, v245
	v_pk_add_f32 v[34:35], v[34:35], v[174:175]
	v_pk_add_f32 v[32:33], v[32:33], v[172:173]
	s_nop 0
	v_cvt_pk_bf16_f32 v32, v32, v33
	v_cvt_pk_bf16_f32 v33, v34, v35
	global_store_dwordx2 v165, v[32:33], s[40:41] offset:288
	v_lshlrev_b32_e32 v168, 16, v246
	v_and_b32_e32 v169, 0xffff0000, v246
	v_lshlrev_b32_e32 v170, 16, v247
	v_and_b32_e32 v171, 0xffff0000, v247
	v_pk_add_f32 v[30:31], v[30:31], v[170:171]
	v_pk_add_f32 v[28:29], v[28:29], v[168:169]
	s_nop 0
	v_cvt_pk_bf16_f32 v28, v28, v29
	v_cvt_pk_bf16_f32 v29, v30, v31
	global_store_dwordx2 v166, v[28:29], s[40:41]
	v_lshlrev_b32_e32 v172, 16, v248
	v_and_b32_e32 v173, 0xffff0000, v248
	v_lshlrev_b32_e32 v174, 16, v249
	v_and_b32_e32 v175, 0xffff0000, v249
	v_pk_add_f32 v[26:27], v[26:27], v[174:175]
	v_pk_add_f32 v[24:25], v[24:25], v[172:173]
	s_nop 0
	v_cvt_pk_bf16_f32 v24, v24, v25
	v_cvt_pk_bf16_f32 v25, v26, v27
	global_store_dwordx2 v166, v[24:25], s[40:41] offset:32
	v_lshlrev_b32_e32 v168, 16, v250
	v_and_b32_e32 v169, 0xffff0000, v250
	v_lshlrev_b32_e32 v170, 16, v251
	v_and_b32_e32 v171, 0xffff0000, v251
	v_pk_add_f32 v[22:23], v[22:23], v[170:171]
	v_pk_add_f32 v[20:21], v[20:21], v[168:169]
	s_nop 0
	v_cvt_pk_bf16_f32 v20, v20, v21
	v_cvt_pk_bf16_f32 v21, v22, v23
	global_store_dwordx2 v166, v[20:21], s[40:41] offset:256
	v_lshlrev_b32_e32 v172, 16, v252
	v_and_b32_e32 v173, 0xffff0000, v252
	v_lshlrev_b32_e32 v174, 16, v253
	v_and_b32_e32 v175, 0xffff0000, v253
	v_pk_add_f32 v[18:19], v[18:19], v[174:175]
	v_pk_add_f32 v[16:17], v[16:17], v[172:173]
	s_nop 0
	v_cvt_pk_bf16_f32 v16, v16, v17
	v_cvt_pk_bf16_f32 v17, v18, v19
	global_store_dwordx2 v166, v[16:17], s[40:41] offset:288
	v_lshlrev_b32_e32 v168, 16, v182
	v_and_b32_e32 v169, 0xffff0000, v182
	v_lshlrev_b32_e32 v170, 16, v183
	v_and_b32_e32 v171, 0xffff0000, v183
	v_pk_add_f32 v[14:15], v[14:15], v[170:171]
	v_pk_add_f32 v[12:13], v[12:13], v[168:169]
	s_nop 0
	v_cvt_pk_bf16_f32 v12, v12, v13
	v_cvt_pk_bf16_f32 v13, v14, v15
	global_store_dwordx2 v167, v[12:13], s[40:41]
	v_lshlrev_b32_e32 v172, 16, v184
	v_and_b32_e32 v173, 0xffff0000, v184
	v_lshlrev_b32_e32 v174, 16, v185
	v_and_b32_e32 v175, 0xffff0000, v185
	v_pk_add_f32 v[10:11], v[10:11], v[174:175]
	v_pk_add_f32 v[8:9], v[8:9], v[172:173]
	s_nop 0
	v_cvt_pk_bf16_f32 v8, v8, v9
	v_cvt_pk_bf16_f32 v9, v10, v11
	global_store_dwordx2 v167, v[8:9], s[40:41] offset:32
	v_lshlrev_b32_e32 v168, 16, v186
	v_and_b32_e32 v169, 0xffff0000, v186
	v_lshlrev_b32_e32 v170, 16, v187
	v_and_b32_e32 v171, 0xffff0000, v187
	v_pk_add_f32 v[6:7], v[6:7], v[170:171]
	v_pk_add_f32 v[4:5], v[4:5], v[168:169]
	s_nop 0
	v_cvt_pk_bf16_f32 v4, v4, v5
	v_cvt_pk_bf16_f32 v5, v6, v7
	global_store_dwordx2 v167, v[4:5], s[40:41] offset:256
	v_lshlrev_b32_e32 v172, 16, v190
	v_and_b32_e32 v173, 0xffff0000, v190
	v_lshlrev_b32_e32 v174, 16, v191
	v_and_b32_e32 v175, 0xffff0000, v191
	v_pk_add_f32 v[2:3], v[2:3], v[174:175]
	v_pk_add_f32 v[0:1], v[0:1], v[172:173]
	s_nop 0
	v_cvt_pk_bf16_f32 v0, v0, v1
	v_cvt_pk_bf16_f32 v1, v2, v3
	global_store_dwordx2 v167, v[0:1], s[40:41] offset:288
	s_and_b64 vcc, exec, s[38:39]
	s_mov_b64 s[16:17], -1
	s_cbranch_vccnz .LBB0_1069

; __device__ __forceinline__ u32x2 pk4(f32x4 v) { u32x2 w; w.x = pk2(v[0], v[1]); w.y = pk2(v[2], v[3]); return w; }
; __device__ __forceinline__ f32x4 ldbf4(const bf16_t* p) { const u32x2 w = *(const u32x2*)p; f32x4 v; v[0] = __uint_as_float(w.x << 16); v[1] = __uint_as_float(w.x & 0xffff0000u); v[2] = __uint_as_float(w.y << 16); v[3] = __uint_as_float(w.y & 0xffff0000u); return v; }
; __device__ __forceinline__ void phase_conv(KP p, int l, int gw, int NGW, int lane) {
;     ...
;     for (int it = gw; it < NRB * 11; it += NGW) {
;         const int rbi = it / 11, sl = it - rbi * 11, rb = NRB - 1 - rbi, r0 = rb * 16, f = sl * 256 + lane * 4;
;         const f32x4 wa0 = *(const f32x4*)(cw + f), wa1 = *(const f32x4*)(cw + DFF2 + f), wa2 = *(const f32x4*)(cw + 2 * DFF2 + f), ba = *(const f32x4*)(cb + f);
;         const f32x4 wg0 = *(const f32x4*)(cw + DFF + f), wg1 = *(const f32x4*)(cw + DFF2 + DFF + f), wg2 = *(const f32x4*)(cw + 2 * DFF2 + DFF + f), bg = *(const f32x4*)(cb + DFF + f);
;         f32x4 a2, a1, g2, g1;
;         if (r0 < RP) { if ((r0 & 4095) == 0) { const bf16_t* m0 = U + (size_t)(RM0 + 14) * DFF2; a2 = ldbf4(m0 + f); g2 = ldbf4(m0 + DFF + f); a1 = ldbf4(m0 + DFF2 + f); g1 = ldbf4(m0 + DFF2 + DFF + f); }
;                        else { const bf16_t* m0 = U + (size_t)(r0 - 2) * DFF2; a2 = ldbf4(m0 + f); g2 = ldbf4(m0 + DFF + f); a1 = ldbf4(m0 + DFF2 + f); g1 = ldbf4(m0 + DFF2 + DFF + f); } }
;         else if (r0 < RS1) { const float* s0 = st + (size_t)((r0 - RS0) >> 4) * 2 * DFF2; a2 = *(const f32x4*)(s0 + f); g2 = *(const f32x4*)(s0 + DFF + f); a1 = *(const f32x4*)(s0 + DFF2 + f); g1 = *(const f32x4*)(s0 + DFF2 + DFF + f); }
;         else { a2 = (f32x4){0.f, 0.f, 0.f, 0.f}; a1 = a2; g2 = a2; g1 = a2; }
; #pragma unroll 4
;         for (int i = 0; i < 16; ++i) { const bf16_t* ur = U + (size_t)(r0 + i) * DFF2; const f32x4 a0 = ldbf4(ur + f), g0 = ldbf4(ur + DFF + f);
;             const f32x4 ca = ba + wa0 * a2 + wa1 * a1 + wa2 * a0, cg = bg + wg0 * g2 + wg1 * g1 + wg2 * g0; f32x4 o;
;             o[0] = ca[0] * cg[0] / (1.f + __expf(-cg[0])); o[1] = ca[1] * cg[1] / (1.f + __expf(-cg[1])); o[2] = ca[2] * cg[2] / (1.f + __expf(-cg[2])); o[3] = ca[3] * cg[3] / (1.f + __expf(-cg[3]));
;             *(u32x2*)(ACT + (size_t)(r0 + i) * DFF + f) = pk4(o);
;             a2 = a1; a1 = a0; g2 = g1; g1 = g0; }
;     }
; }
.LBB0_1377:
	s_mul_i32 s1, s22, 0x1600
	s_mulk_i32 s20, 0xb00
	s_mul_hi_i32 s0, s22, 0x1600
	s_add_u32 s64, s38, s1
	v_subrev_u32_e32 v48, s20, v71
	s_addc_u32 s65, s39, s0
	s_mul_hi_i32 s0, s22, 0x2c00
	s_mulk_i32 s22, 0x2c00
	v_ashrrev_i32_e32 v49, 31, v48
	s_add_u32 s66, s38, s22
	v_lshlrev_b64 v[48:49], 1, v[48:49]
	s_addc_u32 s67, s39, s0
	s_add_u32 s66, s66, 0x53bd0000
	s_addc_u32 s67, s67, 0
	s_add_u32 s22, s66, 0x1600
	s_addc_u32 s23, s67, 0
	s_add_u32 s64, s64, 0x69e90000
	s_addc_u32 s65, s65, 0
	global_load_dwordx2 v[72:73], v48, s[66:67]
	global_load_dwordx2 v[74:75], v48, s[22:23]
	s_add_u32 s66, s66, 0x2c00
	s_addc_u32 s67, s67, 0
	s_add_u32 s22, s22, 0x2c00
	s_addc_u32 s23, s23, 0
	global_load_dwordx2 v[76:77], v48, s[66:67]
	global_load_dwordx2 v[78:79], v48, s[22:23]
	s_add_u32 s66, s66, 0x2c00
	s_addc_u32 s67, s67, 0
	s_add_u32 s22, s22, 0x2c00
	s_addc_u32 s23, s23, 0
	global_load_dwordx2 v[80:81], v48, s[66:67]
	global_load_dwordx2 v[82:83], v48, s[22:23]
	s_add_u32 s66, s66, 0x2c00
	s_addc_u32 s67, s67, 0
	s_add_u32 s22, s22, 0x2c00
	s_addc_u32 s23, s23, 0
	global_load_dwordx2 v[84:85], v48, s[66:67]
	global_load_dwordx2 v[86:87], v48, s[22:23]
	s_add_u32 s66, s66, 0x2c00
	s_addc_u32 s67, s67, 0
	s_add_u32 s22, s22, 0x2c00
	s_addc_u32 s23, s23, 0
	global_load_dwordx2 v[88:89], v48, s[66:67]
	global_load_dwordx2 v[90:91], v48, s[22:23]
	s_add_u32 s66, s66, 0x2c00
	s_addc_u32 s67, s67, 0
	s_add_u32 s22, s22, 0x2c00
	s_addc_u32 s23, s23, 0
	global_load_dwordx2 v[92:93], v48, s[66:67]
	global_load_dwordx2 v[94:95], v48, s[22:23]
	s_add_u32 s66, s66, 0x2c00
	s_addc_u32 s67, s67, 0
	s_add_u32 s22, s22, 0x2c00
	s_addc_u32 s23, s23, 0
	global_load_dwordx2 v[96:97], v48, s[66:67]
	global_load_dwordx2 v[98:99], v48, s[22:23]
	s_add_u32 s66, s66, 0x2c00
	s_addc_u32 s67, s67, 0
	s_add_u32 s22, s22, 0x2c00
	s_addc_u32 s23, s23, 0
	global_load_dwordx2 v[100:101], v48, s[66:67]
	global_load_dwordx2 v[102:103], v48, s[22:23]
	s_add_u32 s66, s66, 0x2c00
	s_addc_u32 s67, s67, 0
	s_add_u32 s22, s22, 0x2c00
	s_addc_u32 s23, s23, 0
	global_load_dwordx2 v[104:105], v48, s[66:67]
	global_load_dwordx2 v[106:107], v48, s[22:23]
	s_add_u32 s66, s66, 0x2c00
	s_addc_u32 s67, s67, 0
	s_add_u32 s22, s22, 0x2c00
	s_addc_u32 s23, s23, 0
	global_load_dwordx2 v[108:109], v48, s[66:67]
	global_load_dwordx2 v[110:111], v48, s[22:23]
	s_add_u32 s66, s66, 0x2c00
	s_addc_u32 s67, s67, 0
	s_add_u32 s22, s22, 0x2c00
	s_addc_u32 s23, s23, 0
	global_load_dwordx2 v[112:113], v48, s[66:67]
	global_load_dwordx2 v[114:115], v48, s[22:23]
	s_add_u32 s66, s66, 0x2c00
	s_addc_u32 s67, s67, 0
	s_add_u32 s22, s22, 0x2c00
	s_addc_u32 s23, s23, 0
	global_load_dwordx2 v[116:117], v48, s[66:67]
	global_load_dwordx2 v[118:119], v48, s[22:23]
	s_add_u32 s66, s66, 0x2c00
	s_addc_u32 s67, s67, 0
	s_add_u32 s22, s22, 0x2c00
	s_addc_u32 s23, s23, 0
	global_load_dwordx2 v[120:121], v48, s[66:67]
	global_load_dwordx2 v[122:123], v48, s[22:23]
	s_add_u32 s66, s66, 0x2c00
	s_addc_u32 s67, s67, 0
	s_add_u32 s22, s22, 0x2c00
	s_addc_u32 s23, s23, 0
	global_load_dwordx2 v[124:125], v48, s[66:67]
	global_load_dwordx2 v[126:127], v48, s[22:23]
	s_add_u32 s66, s66, 0x2c00
	s_addc_u32 s67, s67, 0
	s_add_u32 s22, s22, 0x2c00
	s_addc_u32 s23, s23, 0
	global_load_dwordx2 v[130:131], v48, s[66:67]
	global_load_dwordx2 v[132:133], v48, s[22:23]
	s_add_u32 s66, s66, 0x2c00
	s_addc_u32 s67, s67, 0
	s_add_u32 s22, s22, 0x2c00
	s_addc_u32 s23, s23, 0
	global_load_dwordx2 v[134:135], v48, s[66:67]
	global_load_dwordx2 v[136:137], v48, s[22:23]
	s_waitcnt vmcnt(30)
	v_lshlrev_b32_e32 v52, 16, v72
	v_and_b32_e32 v53, 0xffff0000, v72
	v_lshlrev_b32_e32 v54, 16, v73
	v_and_b32_e32 v55, 0xffff0000, v73
	v_lshlrev_b32_e32 v56, 16, v74
	v_and_b32_e32 v57, 0xffff0000, v74
	v_lshlrev_b32_e32 v58, 16, v75
	v_and_b32_e32 v59, 0xffff0000, v75
	v_pk_fma_f32 v[138:139], v[0:1], v[44:45], v[12:13]
	v_pk_fma_f32 v[140:141], v[2:3], v[46:47], v[14:15]
	v_pk_fma_f32 v[142:143], v[16:17], v[40:41], v[28:29]
	v_pk_fma_f32 v[144:145], v[18:19], v[42:43], v[30:31]
	v_pk_fma_f32 v[138:139], v[4:5], v[32:33], v[138:139]
	v_pk_fma_f32 v[140:141], v[6:7], v[34:35], v[140:141]
	v_pk_fma_f32 v[142:143], v[20:21], v[36:37], v[142:143]
	v_pk_fma_f32 v[144:145], v[22:23], v[38:39], v[144:145]
	v_pk_fma_f32 v[138:139], v[8:9], v[52:53], v[138:139]
	v_pk_fma_f32 v[140:141], v[10:11], v[54:55], v[140:141]
	v_pk_fma_f32 v[142:143], v[24:25], v[56:57], v[142:143]
	v_pk_fma_f32 v[144:145], v[26:27], v[58:59], v[144:145]
	v_mul_f32_e32 v152, 0xbfb8aa3b, v142
	v_mul_f32_e32 v153, 0xbfb8aa3b, v143
	v_mul_f32_e32 v154, 0xbfb8aa3b, v144
	v_mul_f32_e32 v155, 0xbfb8aa3b, v145
	v_exp_f32_e32 v152, v152
	v_exp_f32_e32 v153, v153
	v_exp_f32_e32 v154, v154
	v_exp_f32_e32 v155, v155
	v_add_f32_e32 v152, 1.0, v152
	v_add_f32_e32 v153, 1.0, v153
	v_add_f32_e32 v154, 1.0, v154
	v_add_f32_e32 v155, 1.0, v155
	v_rcp_f32_e32 v152, v152
	v_rcp_f32_e32 v153, v153
	v_rcp_f32_e32 v154, v154
	v_rcp_f32_e32 v155, v155
	v_mul_f32_e32 v156, v138, v142
	v_mul_f32_e32 v157, v139, v143
	v_mul_f32_e32 v158, v140, v144
	v_mul_f32_e32 v159, v141, v145
	v_mul_f32_e32 v156, v156, v152
	v_mul_f32_e32 v157, v157, v153
	v_mul_f32_e32 v158, v158, v154
	v_mul_f32_e32 v159, v159, v155
	v_cvt_pk_bf16_f32 v148, v156, v157
	v_cvt_pk_bf16_f32 v149, v158, v159
	global_store_dwordx2 v48, v[148:149], s[64:65]
	s_add_u32 s64, s64, 0x1600
	s_addc_u32 s65, s65, 0
	s_waitcnt vmcnt(29)
; __device__ __forceinline__ u32x2 pk4(f32x4 v) { u32x2 w; w.x = pk2(v[0], v[1]); w.y = pk2(v[2], v[3]); return w; }
; __device__ __forceinline__ f32x4 ldbf4(const bf16_t* p) { const u32x2 w = *(const u32x2*)p; f32x4 v; v[0] = __uint_as_float(w.x << 16); v[1] = __uint_as_float(w.x & 0xffff0000u); v[2] = __uint_as_float(w.y << 16); v[3] = __uint_as_float(w.y & 0xffff0000u); return v; }
; __device__ __forceinline__ void phase_conv(KP p, int l, int gw, int NGW, int lane) {
;     ...
;         for (int i = 0; i < 16; ++i) { const bf16_t* ur = U + (size_t)(r0 + i) * DFF2; const f32x4 a0 = ldbf4(ur + f), g0 = ldbf4(ur + DFF + f);
;             const f32x4 ca = ba + wa0 * a2 + wa1 * a1 + wa2 * a0, cg = bg + wg0 * g2 + wg1 * g1 + wg2 * g0; f32x4 o;
;             o[0] = ca[0] * cg[0] / (1.f + __expf(-cg[0])); o[1] = ca[1] * cg[1] / (1.f + __expf(-cg[1])); o[2] = ca[2] * cg[2] / (1.f + __expf(-cg[2])); o[3] = ca[3] * cg[3] / (1.f + __expf(-cg[3]));
;             *(u32x2*)(ACT + (size_t)(r0 + i) * DFF + f) = pk4(o);
;             a2 = a1; a1 = a0; g2 = g1; g1 = g0; }
	v_lshlrev_b32_e32 v60, 16, v76
	v_and_b32_e32 v61, 0xffff0000, v76
	v_lshlrev_b32_e32 v62, 16, v77
	v_and_b32_e32 v63, 0xffff0000, v77
	v_lshlrev_b32_e32 v64, 16, v78
	v_and_b32_e32 v65, 0xffff0000, v78
	v_lshlrev_b32_e32 v66, 16, v79
	v_and_b32_e32 v67, 0xffff0000, v79
	v_pk_fma_f32 v[138:139], v[0:1], v[32:33], v[12:13]
	v_pk_fma_f32 v[140:141], v[2:3], v[34:35], v[14:15]
	v_pk_fma_f32 v[142:143], v[16:17], v[36:37], v[28:29]
	v_pk_fma_f32 v[144:145], v[18:19], v[38:39], v[30:31]
	v_pk_fma_f32 v[138:139], v[4:5], v[52:53], v[138:139]
	v_pk_fma_f32 v[140:141], v[6:7], v[54:55], v[140:141]
	v_pk_fma_f32 v[142:143], v[20:21], v[56:57], v[142:143]
	v_pk_fma_f32 v[144:145], v[22:23], v[58:59], v[144:145]
	v_pk_fma_f32 v[138:139], v[8:9], v[60:61], v[138:139]
	v_pk_fma_f32 v[140:141], v[10:11], v[62:63], v[140:141]
	v_pk_fma_f32 v[142:143], v[24:25], v[64:65], v[142:143]
	v_pk_fma_f32 v[144:145], v[26:27], v[66:67], v[144:145]
	v_mul_f32_e32 v152, 0xbfb8aa3b, v142
	v_mul_f32_e32 v153, 0xbfb8aa3b, v143
	v_mul_f32_e32 v154, 0xbfb8aa3b, v144
	v_mul_f32_e32 v155, 0xbfb8aa3b, v145
	v_exp_f32_e32 v152, v152
	v_exp_f32_e32 v153, v153
	v_exp_f32_e32 v154, v154
	v_exp_f32_e32 v155, v155
	v_add_f32_e32 v152, 1.0, v152
	v_add_f32_e32 v153, 1.0, v153
	v_add_f32_e32 v154, 1.0, v154
	v_add_f32_e32 v155, 1.0, v155
	v_rcp_f32_e32 v152, v152
	v_rcp_f32_e32 v153, v153
	v_rcp_f32_e32 v154, v154
	v_rcp_f32_e32 v155, v155
	v_mul_f32_e32 v156, v138, v142
	v_mul_f32_e32 v157, v139, v143
	v_mul_f32_e32 v158, v140, v144
	v_mul_f32_e32 v159, v141, v145
	v_mul_f32_e32 v156, v156, v152
	v_mul_f32_e32 v157, v157, v153
	v_mul_f32_e32 v158, v158, v154
	v_mul_f32_e32 v159, v159, v155
	v_cvt_pk_bf16_f32 v68, v156, v157
	v_cvt_pk_bf16_f32 v69, v158, v159
	global_store_dwordx2 v48, v[68:69], s[64:65]
	s_add_u32 s64, s64, 0x1600
	s_addc_u32 s65, s65, 0
	s_waitcnt vmcnt(28)
	v_lshlrev_b32_e32 v44, 16, v80
	v_and_b32_e32 v45, 0xffff0000, v80
	v_lshlrev_b32_e32 v46, 16, v81
	v_and_b32_e32 v47, 0xffff0000, v81
	v_lshlrev_b32_e32 v40, 16, v82
	v_and_b32_e32 v41, 0xffff0000, v82
	v_lshlrev_b32_e32 v42, 16, v83
	v_and_b32_e32 v43, 0xffff0000, v83
	v_pk_fma_f32 v[138:139], v[0:1], v[52:53], v[12:13]
	v_pk_fma_f32 v[140:141], v[2:3], v[54:55], v[14:15]
	v_pk_fma_f32 v[142:143], v[16:17], v[56:57], v[28:29]
	v_pk_fma_f32 v[144:145], v[18:19], v[58:59], v[30:31]
	v_pk_fma_f32 v[138:139], v[4:5], v[60:61], v[138:139]
	v_pk_fma_f32 v[140:141], v[6:7], v[62:63], v[140:141]
	v_pk_fma_f32 v[142:143], v[20:21], v[64:65], v[142:143]
	v_pk_fma_f32 v[144:145], v[22:23], v[66:67], v[144:145]
	v_pk_fma_f32 v[138:139], v[8:9], v[44:45], v[138:139]
	v_pk_fma_f32 v[140:141], v[10:11], v[46:47], v[140:141]
	v_pk_fma_f32 v[142:143], v[24:25], v[40:41], v[142:143]
	v_pk_fma_f32 v[144:145], v[26:27], v[42:43], v[144:145]
	v_mul_f32_e32 v152, 0xbfb8aa3b, v142
	v_mul_f32_e32 v153, 0xbfb8aa3b, v143
	v_mul_f32_e32 v154, 0xbfb8aa3b, v144
	v_mul_f32_e32 v155, 0xbfb8aa3b, v145
	v_exp_f32_e32 v152, v152
	v_exp_f32_e32 v153, v153
	v_exp_f32_e32 v154, v154
	v_exp_f32_e32 v155, v155
	v_add_f32_e32 v152, 1.0, v152
	v_add_f32_e32 v153, 1.0, v153
	v_add_f32_e32 v154, 1.0, v154
	v_add_f32_e32 v155, 1.0, v155
	v_rcp_f32_e32 v152, v152
	v_rcp_f32_e32 v153, v153
	v_rcp_f32_e32 v154, v154
	v_rcp_f32_e32 v155, v155
	v_mul_f32_e32 v156, v138, v142
	v_mul_f32_e32 v157, v139, v143
	v_mul_f32_e32 v158, v140, v144
	v_mul_f32_e32 v159, v141, v145
	v_mul_f32_e32 v156, v156, v152
	v_mul_f32_e32 v157, v157, v153
	v_mul_f32_e32 v158, v158, v154
	v_mul_f32_e32 v159, v159, v155
	v_cvt_pk_bf16_f32 v148, v156, v157
	v_cvt_pk_bf16_f32 v149, v158, v159
	global_store_dwordx2 v48, v[148:149], s[64:65]
	s_add_u32 s64, s64, 0x1600
	s_addc_u32 s65, s65, 0
	s_waitcnt vmcnt(27)
	v_lshlrev_b32_e32 v32, 16, v84
	v_and_b32_e32 v33, 0xffff0000, v84
	v_lshlrev_b32_e32 v34, 16, v85
	v_and_b32_e32 v35, 0xffff0000, v85
	v_lshlrev_b32_e32 v36, 16, v86
	v_and_b32_e32 v37, 0xffff0000, v86
	v_lshlrev_b32_e32 v38, 16, v87
	v_and_b32_e32 v39, 0xffff0000, v87
	v_pk_fma_f32 v[138:139], v[0:1], v[60:61], v[12:13]
	v_pk_fma_f32 v[140:141], v[2:3], v[62:63], v[14:15]
	v_pk_fma_f32 v[142:143], v[16:17], v[64:65], v[28:29]
	v_pk_fma_f32 v[144:145], v[18:19], v[66:67], v[30:31]
	v_pk_fma_f32 v[138:139], v[4:5], v[44:45], v[138:139]
	v_pk_fma_f32 v[140:141], v[6:7], v[46:47], v[140:141]
	v_pk_fma_f32 v[142:143], v[20:21], v[40:41], v[142:143]
	v_pk_fma_f32 v[144:145], v[22:23], v[42:43], v[144:145]
	v_pk_fma_f32 v[138:139], v[8:9], v[32:33], v[138:139]
	v_pk_fma_f32 v[140:141], v[10:11], v[34:35], v[140:141]
	v_pk_fma_f32 v[142:143], v[24:25], v[36:37], v[142:143]
	v_pk_fma_f32 v[144:145], v[26:27], v[38:39], v[144:145]
	v_mul_f32_e32 v152, 0xbfb8aa3b, v142
	v_mul_f32_e32 v153, 0xbfb8aa3b, v143
	v_mul_f32_e32 v154, 0xbfb8aa3b, v144
	v_mul_f32_e32 v155, 0xbfb8aa3b, v145
	v_exp_f32_e32 v152, v152
	v_exp_f32_e32 v153, v153
	v_exp_f32_e32 v154, v154
	v_exp_f32_e32 v155, v155
	v_add_f32_e32 v152, 1.0, v152
	v_add_f32_e32 v153, 1.0, v153
	v_add_f32_e32 v154, 1.0, v154
	v_add_f32_e32 v155, 1.0, v155
	v_rcp_f32_e32 v152, v152
	v_rcp_f32_e32 v153, v153
	v_rcp_f32_e32 v154, v154
	v_rcp_f32_e32 v155, v155
	v_mul_f32_e32 v156, v138, v142
	v_mul_f32_e32 v157, v139, v143
	v_mul_f32_e32 v158, v140, v144
	v_mul_f32_e32 v159, v141, v145
	v_mul_f32_e32 v156, v156, v152
	v_mul_f32_e32 v157, v157, v153
	v_mul_f32_e32 v158, v158, v154
	v_mul_f32_e32 v159, v159, v155
	v_cvt_pk_bf16_f32 v68, v156, v157
	v_cvt_pk_bf16_f32 v69, v158, v159
	global_store_dwordx2 v48, v[68:69], s[64:65]
	s_add_u32 s64, s64, 0x1600
	s_addc_u32 s65, s65, 0
	s_waitcnt vmcnt(26)
; __device__ __forceinline__ u32x2 pk4(f32x4 v) { u32x2 w; w.x = pk2(v[0], v[1]); w.y = pk2(v[2], v[3]); return w; }
; __device__ __forceinline__ f32x4 ldbf4(const bf16_t* p) { const u32x2 w = *(const u32x2*)p; f32x4 v; v[0] = __uint_as_float(w.x << 16); v[1] = __uint_as_float(w.x & 0xffff0000u); v[2] = __uint_as_float(w.y << 16); v[3] = __uint_as_float(w.y & 0xffff0000u); return v; }
; __device__ __forceinline__ void phase_conv(KP p, int l, int gw, int NGW, int lane) {
;     ...
;         for (int i = 0; i < 16; ++i) { const bf16_t* ur = U + (size_t)(r0 + i) * DFF2; const f32x4 a0 = ldbf4(ur + f), g0 = ldbf4(ur + DFF + f);
;             const f32x4 ca = ba + wa0 * a2 + wa1 * a1 + wa2 * a0, cg = bg + wg0 * g2 + wg1 * g1 + wg2 * g0; f32x4 o;
;             o[0] = ca[0] * cg[0] / (1.f + __expf(-cg[0])); o[1] = ca[1] * cg[1] / (1.f + __expf(-cg[1])); o[2] = ca[2] * cg[2] / (1.f + __expf(-cg[2])); o[3] = ca[3] * cg[3] / (1.f + __expf(-cg[3]));
;             *(u32x2*)(ACT + (size_t)(r0 + i) * DFF + f) = pk4(o);
;             a2 = a1; a1 = a0; g2 = g1; g1 = g0; }
	v_lshlrev_b32_e32 v52, 16, v88
	v_and_b32_e32 v53, 0xffff0000, v88
	v_lshlrev_b32_e32 v54, 16, v89
	v_and_b32_e32 v55, 0xffff0000, v89
	v_lshlrev_b32_e32 v56, 16, v90
	v_and_b32_e32 v57, 0xffff0000, v90
	v_lshlrev_b32_e32 v58, 16, v91
	v_and_b32_e32 v59, 0xffff0000, v91
	v_pk_fma_f32 v[138:139], v[0:1], v[44:45], v[12:13]
	v_pk_fma_f32 v[140:141], v[2:3], v[46:47], v[14:15]
	v_pk_fma_f32 v[142:143], v[16:17], v[40:41], v[28:29]
	v_pk_fma_f32 v[144:145], v[18:19], v[42:43], v[30:31]
	v_pk_fma_f32 v[138:139], v[4:5], v[32:33], v[138:139]
	v_pk_fma_f32 v[140:141], v[6:7], v[34:35], v[140:141]
	v_pk_fma_f32 v[142:143], v[20:21], v[36:37], v[142:143]
	v_pk_fma_f32 v[144:145], v[22:23], v[38:39], v[144:145]
	v_pk_fma_f32 v[138:139], v[8:9], v[52:53], v[138:139]
	v_pk_fma_f32 v[140:141], v[10:11], v[54:55], v[140:141]
	v_pk_fma_f32 v[142:143], v[24:25], v[56:57], v[142:143]
	v_pk_fma_f32 v[144:145], v[26:27], v[58:59], v[144:145]
	v_mul_f32_e32 v152, 0xbfb8aa3b, v142
	v_mul_f32_e32 v153, 0xbfb8aa3b, v143
	v_mul_f32_e32 v154, 0xbfb8aa3b, v144
	v_mul_f32_e32 v155, 0xbfb8aa3b, v145
	v_exp_f32_e32 v152, v152
	v_exp_f32_e32 v153, v153
	v_exp_f32_e32 v154, v154
	v_exp_f32_e32 v155, v155
	v_add_f32_e32 v152, 1.0, v152
	v_add_f32_e32 v153, 1.0, v153
	v_add_f32_e32 v154, 1.0, v154
	v_add_f32_e32 v155, 1.0, v155
	v_rcp_f32_e32 v152, v152
	v_rcp_f32_e32 v153, v153
	v_rcp_f32_e32 v154, v154
	v_rcp_f32_e32 v155, v155
	v_mul_f32_e32 v156, v138, v142
	v_mul_f32_e32 v157, v139, v143
	v_mul_f32_e32 v158, v140, v144
	v_mul_f32_e32 v159, v141, v145
	v_mul_f32_e32 v156, v156, v152
	v_mul_f32_e32 v157, v157, v153
	v_mul_f32_e32 v158, v158, v154
	v_mul_f32_e32 v159, v159, v155
	v_cvt_pk_bf16_f32 v148, v156, v157
	v_cvt_pk_bf16_f32 v149, v158, v159
	global_store_dwordx2 v48, v[148:149], s[64:65]
	s_add_u32 s64, s64, 0x1600
	s_addc_u32 s65, s65, 0
	s_waitcnt vmcnt(25)
	v_lshlrev_b32_e32 v60, 16, v92
	v_and_b32_e32 v61, 0xffff0000, v92
	v_lshlrev_b32_e32 v62, 16, v93
	v_and_b32_e32 v63, 0xffff0000, v93
	v_lshlrev_b32_e32 v64, 16, v94
	v_and_b32_e32 v65, 0xffff0000, v94
	v_lshlrev_b32_e32 v66, 16, v95
	v_and_b32_e32 v67, 0xffff0000, v95
	v_pk_fma_f32 v[138:139], v[0:1], v[32:33], v[12:13]
	v_pk_fma_f32 v[140:141], v[2:3], v[34:35], v[14:15]
	v_pk_fma_f32 v[142:143], v[16:17], v[36:37], v[28:29]
	v_pk_fma_f32 v[144:145], v[18:19], v[38:39], v[30:31]
	v_pk_fma_f32 v[138:139], v[4:5], v[52:53], v[138:139]
	v_pk_fma_f32 v[140:141], v[6:7], v[54:55], v[140:141]
	v_pk_fma_f32 v[142:143], v[20:21], v[56:57], v[142:143]
	v_pk_fma_f32 v[144:145], v[22:23], v[58:59], v[144:145]
	v_pk_fma_f32 v[138:139], v[8:9], v[60:61], v[138:139]
	v_pk_fma_f32 v[140:141], v[10:11], v[62:63], v[140:141]
	v_pk_fma_f32 v[142:143], v[24:25], v[64:65], v[142:143]
	v_pk_fma_f32 v[144:145], v[26:27], v[66:67], v[144:145]
	v_mul_f32_e32 v152, 0xbfb8aa3b, v142
	v_mul_f32_e32 v153, 0xbfb8aa3b, v143
	v_mul_f32_e32 v154, 0xbfb8aa3b, v144
	v_mul_f32_e32 v155, 0xbfb8aa3b, v145
	v_exp_f32_e32 v152, v152
	v_exp_f32_e32 v153, v153
	v_exp_f32_e32 v154, v154
	v_exp_f32_e32 v155, v155
	v_add_f32_e32 v152, 1.0, v152
	v_add_f32_e32 v153, 1.0, v153
	v_add_f32_e32 v154, 1.0, v154
	v_add_f32_e32 v155, 1.0, v155
	v_rcp_f32_e32 v152, v152
	v_rcp_f32_e32 v153, v153
	v_rcp_f32_e32 v154, v154
	v_rcp_f32_e32 v155, v155
	v_mul_f32_e32 v156, v138, v142
	v_mul_f32_e32 v157, v139, v143
	v_mul_f32_e32 v158, v140, v144
	v_mul_f32_e32 v159, v141, v145
	v_mul_f32_e32 v156, v156, v152
	v_mul_f32_e32 v157, v157, v153
	v_mul_f32_e32 v158, v158, v154
	v_mul_f32_e32 v159, v159, v155
	v_cvt_pk_bf16_f32 v68, v156, v157
	v_cvt_pk_bf16_f32 v69, v158, v159
	global_store_dwordx2 v48, v[68:69], s[64:65]
	s_add_u32 s64, s64, 0x1600
	s_addc_u32 s65, s65, 0
	s_waitcnt vmcnt(24)
	v_lshlrev_b32_e32 v44, 16, v96
	v_and_b32_e32 v45, 0xffff0000, v96
	v_lshlrev_b32_e32 v46, 16, v97
	v_and_b32_e32 v47, 0xffff0000, v97
	v_lshlrev_b32_e32 v40, 16, v98
	v_and_b32_e32 v41, 0xffff0000, v98
	v_lshlrev_b32_e32 v42, 16, v99
	v_and_b32_e32 v43, 0xffff0000, v99
	v_pk_fma_f32 v[138:139], v[0:1], v[52:53], v[12:13]
	v_pk_fma_f32 v[140:141], v[2:3], v[54:55], v[14:15]
	v_pk_fma_f32 v[142:143], v[16:17], v[56:57], v[28:29]
	v_pk_fma_f32 v[144:145], v[18:19], v[58:59], v[30:31]
	v_pk_fma_f32 v[138:139], v[4:5], v[60:61], v[138:139]
	v_pk_fma_f32 v[140:141], v[6:7], v[62:63], v[140:141]
	v_pk_fma_f32 v[142:143], v[20:21], v[64:65], v[142:143]
	v_pk_fma_f32 v[144:145], v[22:23], v[66:67], v[144:145]
	v_pk_fma_f32 v[138:139], v[8:9], v[44:45], v[138:139]
	v_pk_fma_f32 v[140:141], v[10:11], v[46:47], v[140:141]
	v_pk_fma_f32 v[142:143], v[24:25], v[40:41], v[142:143]
	v_pk_fma_f32 v[144:145], v[26:27], v[42:43], v[144:145]
	v_mul_f32_e32 v152, 0xbfb8aa3b, v142
	v_mul_f32_e32 v153, 0xbfb8aa3b, v143
	v_mul_f32_e32 v154, 0xbfb8aa3b, v144
	v_mul_f32_e32 v155, 0xbfb8aa3b, v145
	v_exp_f32_e32 v152, v152
	v_exp_f32_e32 v153, v153
	v_exp_f32_e32 v154, v154
	v_exp_f32_e32 v155, v155
	v_add_f32_e32 v152, 1.0, v152
	v_add_f32_e32 v153, 1.0, v153
	v_add_f32_e32 v154, 1.0, v154
	v_add_f32_e32 v155, 1.0, v155
	v_rcp_f32_e32 v152, v152
	v_rcp_f32_e32 v153, v153
	v_rcp_f32_e32 v154, v154
	v_rcp_f32_e32 v155, v155
	v_mul_f32_e32 v156, v138, v142
	v_mul_f32_e32 v157, v139, v143
	v_mul_f32_e32 v158, v140, v144
	v_mul_f32_e32 v159, v141, v145
	v_mul_f32_e32 v156, v156, v152
	v_mul_f32_e32 v157, v157, v153
	v_mul_f32_e32 v158, v158, v154
	v_mul_f32_e32 v159, v159, v155
	v_cvt_pk_bf16_f32 v148, v156, v157
	v_cvt_pk_bf16_f32 v149, v158, v159
	global_store_dwordx2 v48, v[148:149], s[64:65]
	s_add_u32 s64, s64, 0x1600
	s_addc_u32 s65, s65, 0
	s_waitcnt vmcnt(23)
; __device__ __forceinline__ u32x2 pk4(f32x4 v) { u32x2 w; w.x = pk2(v[0], v[1]); w.y = pk2(v[2], v[3]); return w; }
; __device__ __forceinline__ f32x4 ldbf4(const bf16_t* p) { const u32x2 w = *(const u32x2*)p; f32x4 v; v[0] = __uint_as_float(w.x << 16); v[1] = __uint_as_float(w.x & 0xffff0000u); v[2] = __uint_as_float(w.y << 16); v[3] = __uint_as_float(w.y & 0xffff0000u); return v; }
; __device__ __forceinline__ void phase_conv(KP p, int l, int gw, int NGW, int lane) {
;     ...
;         for (int i = 0; i < 16; ++i) { const bf16_t* ur = U + (size_t)(r0 + i) * DFF2; const f32x4 a0 = ldbf4(ur + f), g0 = ldbf4(ur + DFF + f);
;             const f32x4 ca = ba + wa0 * a2 + wa1 * a1 + wa2 * a0, cg = bg + wg0 * g2 + wg1 * g1 + wg2 * g0; f32x4 o;
;             o[0] = ca[0] * cg[0] / (1.f + __expf(-cg[0])); o[1] = ca[1] * cg[1] / (1.f + __expf(-cg[1])); o[2] = ca[2] * cg[2] / (1.f + __expf(-cg[2])); o[3] = ca[3] * cg[3] / (1.f + __expf(-cg[3]));
;             *(u32x2*)(ACT + (size_t)(r0 + i) * DFF + f) = pk4(o);
;             a2 = a1; a1 = a0; g2 = g1; g1 = g0; }
	v_lshlrev_b32_e32 v32, 16, v100
	v_and_b32_e32 v33, 0xffff0000, v100
	v_lshlrev_b32_e32 v34, 16, v101
	v_and_b32_e32 v35, 0xffff0000, v101
	v_lshlrev_b32_e32 v36, 16, v102
	v_and_b32_e32 v37, 0xffff0000, v102
	v_lshlrev_b32_e32 v38, 16, v103
	v_and_b32_e32 v39, 0xffff0000, v103
	v_pk_fma_f32 v[138:139], v[0:1], v[60:61], v[12:13]
	v_pk_fma_f32 v[140:141], v[2:3], v[62:63], v[14:15]
	v_pk_fma_f32 v[142:143], v[16:17], v[64:65], v[28:29]
	v_pk_fma_f32 v[144:145], v[18:19], v[66:67], v[30:31]
	v_pk_fma_f32 v[138:139], v[4:5], v[44:45], v[138:139]
	v_pk_fma_f32 v[140:141], v[6:7], v[46:47], v[140:141]
	v_pk_fma_f32 v[142:143], v[20:21], v[40:41], v[142:143]
	v_pk_fma_f32 v[144:145], v[22:23], v[42:43], v[144:145]
	v_pk_fma_f32 v[138:139], v[8:9], v[32:33], v[138:139]
	v_pk_fma_f32 v[140:141], v[10:11], v[34:35], v[140:141]
	v_pk_fma_f32 v[142:143], v[24:25], v[36:37], v[142:143]
	v_pk_fma_f32 v[144:145], v[26:27], v[38:39], v[144:145]
	v_mul_f32_e32 v152, 0xbfb8aa3b, v142
	v_mul_f32_e32 v153, 0xbfb8aa3b, v143
	v_mul_f32_e32 v154, 0xbfb8aa3b, v144
	v_mul_f32_e32 v155, 0xbfb8aa3b, v145
	v_exp_f32_e32 v152, v152
	v_exp_f32_e32 v153, v153
	v_exp_f32_e32 v154, v154
	v_exp_f32_e32 v155, v155
	v_add_f32_e32 v152, 1.0, v152
	v_add_f32_e32 v153, 1.0, v153
	v_add_f32_e32 v154, 1.0, v154
	v_add_f32_e32 v155, 1.0, v155
	v_rcp_f32_e32 v152, v152
	v_rcp_f32_e32 v153, v153
	v_rcp_f32_e32 v154, v154
	v_rcp_f32_e32 v155, v155
	v_mul_f32_e32 v156, v138, v142
	v_mul_f32_e32 v157, v139, v143
	v_mul_f32_e32 v158, v140, v144
	v_mul_f32_e32 v159, v141, v145
	v_mul_f32_e32 v156, v156, v152
	v_mul_f32_e32 v157, v157, v153
	v_mul_f32_e32 v158, v158, v154
	v_mul_f32_e32 v159, v159, v155
	v_cvt_pk_bf16_f32 v68, v156, v157
	v_cvt_pk_bf16_f32 v69, v158, v159
	global_store_dwordx2 v48, v[68:69], s[64:65]
	s_add_u32 s64, s64, 0x1600
	s_addc_u32 s65, s65, 0
	s_waitcnt vmcnt(22)
	v_lshlrev_b32_e32 v52, 16, v104
	v_and_b32_e32 v53, 0xffff0000, v104
	v_lshlrev_b32_e32 v54, 16, v105
	v_and_b32_e32 v55, 0xffff0000, v105
	v_lshlrev_b32_e32 v56, 16, v106
	v_and_b32_e32 v57, 0xffff0000, v106
	v_lshlrev_b32_e32 v58, 16, v107
	v_and_b32_e32 v59, 0xffff0000, v107
	v_pk_fma_f32 v[138:139], v[0:1], v[44:45], v[12:13]
	v_pk_fma_f32 v[140:141], v[2:3], v[46:47], v[14:15]
	v_pk_fma_f32 v[142:143], v[16:17], v[40:41], v[28:29]
	v_pk_fma_f32 v[144:145], v[18:19], v[42:43], v[30:31]
	v_pk_fma_f32 v[138:139], v[4:5], v[32:33], v[138:139]
	v_pk_fma_f32 v[140:141], v[6:7], v[34:35], v[140:141]
	v_pk_fma_f32 v[142:143], v[20:21], v[36:37], v[142:143]
	v_pk_fma_f32 v[144:145], v[22:23], v[38:39], v[144:145]
	v_pk_fma_f32 v[138:139], v[8:9], v[52:53], v[138:139]
	v_pk_fma_f32 v[140:141], v[10:11], v[54:55], v[140:141]
	v_pk_fma_f32 v[142:143], v[24:25], v[56:57], v[142:143]
	v_pk_fma_f32 v[144:145], v[26:27], v[58:59], v[144:145]
	v_mul_f32_e32 v152, 0xbfb8aa3b, v142
	v_mul_f32_e32 v153, 0xbfb8aa3b, v143
	v_mul_f32_e32 v154, 0xbfb8aa3b, v144
	v_mul_f32_e32 v155, 0xbfb8aa3b, v145
	v_exp_f32_e32 v152, v152
	v_exp_f32_e32 v153, v153
	v_exp_f32_e32 v154, v154
	v_exp_f32_e32 v155, v155
	v_add_f32_e32 v152, 1.0, v152
	v_add_f32_e32 v153, 1.0, v153
	v_add_f32_e32 v154, 1.0, v154
	v_add_f32_e32 v155, 1.0, v155
	v_rcp_f32_e32 v152, v152
	v_rcp_f32_e32 v153, v153
	v_rcp_f32_e32 v154, v154
	v_rcp_f32_e32 v155, v155
	v_mul_f32_e32 v156, v138, v142
	v_mul_f32_e32 v157, v139, v143
	v_mul_f32_e32 v158, v140, v144
	v_mul_f32_e32 v159, v141, v145
	v_mul_f32_e32 v156, v156, v152
	v_mul_f32_e32 v157, v157, v153
	v_mul_f32_e32 v158, v158, v154
	v_mul_f32_e32 v159, v159, v155
	v_cvt_pk_bf16_f32 v148, v156, v157
	v_cvt_pk_bf16_f32 v149, v158, v159
	global_store_dwordx2 v48, v[148:149], s[64:65]
	s_add_u32 s64, s64, 0x1600
	s_addc_u32 s65, s65, 0
	s_waitcnt vmcnt(21)
	v_lshlrev_b32_e32 v60, 16, v108
	v_and_b32_e32 v61, 0xffff0000, v108
	v_lshlrev_b32_e32 v62, 16, v109
	v_and_b32_e32 v63, 0xffff0000, v109
	v_lshlrev_b32_e32 v64, 16, v110
	v_and_b32_e32 v65, 0xffff0000, v110
	v_lshlrev_b32_e32 v66, 16, v111
	v_and_b32_e32 v67, 0xffff0000, v111
	v_pk_fma_f32 v[138:139], v[0:1], v[32:33], v[12:13]
	v_pk_fma_f32 v[140:141], v[2:3], v[34:35], v[14:15]
	v_pk_fma_f32 v[142:143], v[16:17], v[36:37], v[28:29]
	v_pk_fma_f32 v[144:145], v[18:19], v[38:39], v[30:31]
	v_pk_fma_f32 v[138:139], v[4:5], v[52:53], v[138:139]
	v_pk_fma_f32 v[140:141], v[6:7], v[54:55], v[140:141]
	v_pk_fma_f32 v[142:143], v[20:21], v[56:57], v[142:143]
	v_pk_fma_f32 v[144:145], v[22:23], v[58:59], v[144:145]
	v_pk_fma_f32 v[138:139], v[8:9], v[60:61], v[138:139]
	v_pk_fma_f32 v[140:141], v[10:11], v[62:63], v[140:141]
	v_pk_fma_f32 v[142:143], v[24:25], v[64:65], v[142:143]
	v_pk_fma_f32 v[144:145], v[26:27], v[66:67], v[144:145]
	v_mul_f32_e32 v152, 0xbfb8aa3b, v142
	v_mul_f32_e32 v153, 0xbfb8aa3b, v143
	v_mul_f32_e32 v154, 0xbfb8aa3b, v144
	v_mul_f32_e32 v155, 0xbfb8aa3b, v145
	v_exp_f32_e32 v152, v152
	v_exp_f32_e32 v153, v153
	v_exp_f32_e32 v154, v154
	v_exp_f32_e32 v155, v155
	v_add_f32_e32 v152, 1.0, v152
	v_add_f32_e32 v153, 1.0, v153
	v_add_f32_e32 v154, 1.0, v154
	v_add_f32_e32 v155, 1.0, v155
	v_rcp_f32_e32 v152, v152
	v_rcp_f32_e32 v153, v153
	v_rcp_f32_e32 v154, v154
	v_rcp_f32_e32 v155, v155
	v_mul_f32_e32 v156, v138, v142
	v_mul_f32_e32 v157, v139, v143
	v_mul_f32_e32 v158, v140, v144
	v_mul_f32_e32 v159, v141, v145
	v_mul_f32_e32 v156, v156, v152
	v_mul_f32_e32 v157, v157, v153
	v_mul_f32_e32 v158, v158, v154
	v_mul_f32_e32 v159, v159, v155
	v_cvt_pk_bf16_f32 v68, v156, v157
	v_cvt_pk_bf16_f32 v69, v158, v159
	global_store_dwordx2 v48, v[68:69], s[64:65]
	s_add_u32 s64, s64, 0x1600
	s_addc_u32 s65, s65, 0
	s_waitcnt vmcnt(20)
; __device__ __forceinline__ u32x2 pk4(f32x4 v) { u32x2 w; w.x = pk2(v[0], v[1]); w.y = pk2(v[2], v[3]); return w; }
; __device__ __forceinline__ f32x4 ldbf4(const bf16_t* p) { const u32x2 w = *(const u32x2*)p; f32x4 v; v[0] = __uint_as_float(w.x << 16); v[1] = __uint_as_float(w.x & 0xffff0000u); v[2] = __uint_as_float(w.y << 16); v[3] = __uint_as_float(w.y & 0xffff0000u); return v; }
; __device__ __forceinline__ void phase_conv(KP p, int l, int gw, int NGW, int lane) {
;     ...
;         for (int i = 0; i < 16; ++i) { const bf16_t* ur = U + (size_t)(r0 + i) * DFF2; const f32x4 a0 = ldbf4(ur + f), g0 = ldbf4(ur + DFF + f);
;             const f32x4 ca = ba + wa0 * a2 + wa1 * a1 + wa2 * a0, cg = bg + wg0 * g2 + wg1 * g1 + wg2 * g0; f32x4 o;
;             o[0] = ca[0] * cg[0] / (1.f + __expf(-cg[0])); o[1] = ca[1] * cg[1] / (1.f + __expf(-cg[1])); o[2] = ca[2] * cg[2] / (1.f + __expf(-cg[2])); o[3] = ca[3] * cg[3] / (1.f + __expf(-cg[3]));
;             *(u32x2*)(ACT + (size_t)(r0 + i) * DFF + f) = pk4(o);
;             a2 = a1; a1 = a0; g2 = g1; g1 = g0; }
	v_lshlrev_b32_e32 v44, 16, v112
	v_and_b32_e32 v45, 0xffff0000, v112
	v_lshlrev_b32_e32 v46, 16, v113
	v_and_b32_e32 v47, 0xffff0000, v113
	v_lshlrev_b32_e32 v40, 16, v114
	v_and_b32_e32 v41, 0xffff0000, v114
	v_lshlrev_b32_e32 v42, 16, v115
	v_and_b32_e32 v43, 0xffff0000, v115
	v_pk_fma_f32 v[138:139], v[0:1], v[52:53], v[12:13]
	v_pk_fma_f32 v[140:141], v[2:3], v[54:55], v[14:15]
	v_pk_fma_f32 v[142:143], v[16:17], v[56:57], v[28:29]
	v_pk_fma_f32 v[144:145], v[18:19], v[58:59], v[30:31]
	v_pk_fma_f32 v[138:139], v[4:5], v[60:61], v[138:139]
	v_pk_fma_f32 v[140:141], v[6:7], v[62:63], v[140:141]
	v_pk_fma_f32 v[142:143], v[20:21], v[64:65], v[142:143]
	v_pk_fma_f32 v[144:145], v[22:23], v[66:67], v[144:145]
	v_pk_fma_f32 v[138:139], v[8:9], v[44:45], v[138:139]
	v_pk_fma_f32 v[140:141], v[10:11], v[46:47], v[140:141]
	v_pk_fma_f32 v[142:143], v[24:25], v[40:41], v[142:143]
	v_pk_fma_f32 v[144:145], v[26:27], v[42:43], v[144:145]
	v_mul_f32_e32 v152, 0xbfb8aa3b, v142
	v_mul_f32_e32 v153, 0xbfb8aa3b, v143
	v_mul_f32_e32 v154, 0xbfb8aa3b, v144
	v_mul_f32_e32 v155, 0xbfb8aa3b, v145
	v_exp_f32_e32 v152, v152
	v_exp_f32_e32 v153, v153
	v_exp_f32_e32 v154, v154
	v_exp_f32_e32 v155, v155
	v_add_f32_e32 v152, 1.0, v152
	v_add_f32_e32 v153, 1.0, v153
	v_add_f32_e32 v154, 1.0, v154
	v_add_f32_e32 v155, 1.0, v155
	v_rcp_f32_e32 v152, v152
	v_rcp_f32_e32 v153, v153
	v_rcp_f32_e32 v154, v154
	v_rcp_f32_e32 v155, v155
	v_mul_f32_e32 v156, v138, v142
	v_mul_f32_e32 v157, v139, v143
	v_mul_f32_e32 v158, v140, v144
	v_mul_f32_e32 v159, v141, v145
	v_mul_f32_e32 v156, v156, v152
	v_mul_f32_e32 v157, v157, v153
	v_mul_f32_e32 v158, v158, v154
	v_mul_f32_e32 v159, v159, v155
	v_cvt_pk_bf16_f32 v148, v156, v157
	v_cvt_pk_bf16_f32 v149, v158, v159
	global_store_dwordx2 v48, v[148:149], s[64:65]
	s_add_u32 s64, s64, 0x1600
	s_addc_u32 s65, s65, 0
	s_waitcnt vmcnt(19)
	v_lshlrev_b32_e32 v32, 16, v116
	v_and_b32_e32 v33, 0xffff0000, v116
	v_lshlrev_b32_e32 v34, 16, v117
	v_and_b32_e32 v35, 0xffff0000, v117
	v_lshlrev_b32_e32 v36, 16, v118
	v_and_b32_e32 v37, 0xffff0000, v118
	v_lshlrev_b32_e32 v38, 16, v119
	v_and_b32_e32 v39, 0xffff0000, v119
	v_pk_fma_f32 v[138:139], v[0:1], v[60:61], v[12:13]
	v_pk_fma_f32 v[140:141], v[2:3], v[62:63], v[14:15]
	v_pk_fma_f32 v[142:143], v[16:17], v[64:65], v[28:29]
	v_pk_fma_f32 v[144:145], v[18:19], v[66:67], v[30:31]
	v_pk_fma_f32 v[138:139], v[4:5], v[44:45], v[138:139]
	v_pk_fma_f32 v[140:141], v[6:7], v[46:47], v[140:141]
	v_pk_fma_f32 v[142:143], v[20:21], v[40:41], v[142:143]
	v_pk_fma_f32 v[144:145], v[22:23], v[42:43], v[144:145]
	v_pk_fma_f32 v[138:139], v[8:9], v[32:33], v[138:139]
	v_pk_fma_f32 v[140:141], v[10:11], v[34:35], v[140:141]
	v_pk_fma_f32 v[142:143], v[24:25], v[36:37], v[142:143]
	v_pk_fma_f32 v[144:145], v[26:27], v[38:39], v[144:145]
	v_mul_f32_e32 v152, 0xbfb8aa3b, v142
	v_mul_f32_e32 v153, 0xbfb8aa3b, v143
	v_mul_f32_e32 v154, 0xbfb8aa3b, v144
	v_mul_f32_e32 v155, 0xbfb8aa3b, v145
	v_exp_f32_e32 v152, v152
	v_exp_f32_e32 v153, v153
	v_exp_f32_e32 v154, v154
	v_exp_f32_e32 v155, v155
	v_add_f32_e32 v152, 1.0, v152
	v_add_f32_e32 v153, 1.0, v153
	v_add_f32_e32 v154, 1.0, v154
	v_add_f32_e32 v155, 1.0, v155
	v_rcp_f32_e32 v152, v152
	v_rcp_f32_e32 v153, v153
	v_rcp_f32_e32 v154, v154
	v_rcp_f32_e32 v155, v155
	v_mul_f32_e32 v156, v138, v142
	v_mul_f32_e32 v157, v139, v143
	v_mul_f32_e32 v158, v140, v144
	v_mul_f32_e32 v159, v141, v145
	v_mul_f32_e32 v156, v156, v152
	v_mul_f32_e32 v157, v157, v153
	v_mul_f32_e32 v158, v158, v154
	v_mul_f32_e32 v159, v159, v155
	v_cvt_pk_bf16_f32 v68, v156, v157
	v_cvt_pk_bf16_f32 v69, v158, v159
	global_store_dwordx2 v48, v[68:69], s[64:65]
	s_add_u32 s64, s64, 0x1600
	s_addc_u32 s65, s65, 0
	s_waitcnt vmcnt(18)
	v_lshlrev_b32_e32 v52, 16, v120
	v_and_b32_e32 v53, 0xffff0000, v120
	v_lshlrev_b32_e32 v54, 16, v121
	v_and_b32_e32 v55, 0xffff0000, v121
	v_lshlrev_b32_e32 v56, 16, v122
	v_and_b32_e32 v57, 0xffff0000, v122
	v_lshlrev_b32_e32 v58, 16, v123
	v_and_b32_e32 v59, 0xffff0000, v123
	v_pk_fma_f32 v[138:139], v[0:1], v[44:45], v[12:13]
	v_pk_fma_f32 v[140:141], v[2:3], v[46:47], v[14:15]
	v_pk_fma_f32 v[142:143], v[16:17], v[40:41], v[28:29]
	v_pk_fma_f32 v[144:145], v[18:19], v[42:43], v[30:31]
	v_pk_fma_f32 v[138:139], v[4:5], v[32:33], v[138:139]
	v_pk_fma_f32 v[140:141], v[6:7], v[34:35], v[140:141]
	v_pk_fma_f32 v[142:143], v[20:21], v[36:37], v[142:143]
	v_pk_fma_f32 v[144:145], v[22:23], v[38:39], v[144:145]
	v_pk_fma_f32 v[138:139], v[8:9], v[52:53], v[138:139]
	v_pk_fma_f32 v[140:141], v[10:11], v[54:55], v[140:141]
	v_pk_fma_f32 v[142:143], v[24:25], v[56:57], v[142:143]
	v_pk_fma_f32 v[144:145], v[26:27], v[58:59], v[144:145]
	v_mul_f32_e32 v152, 0xbfb8aa3b, v142
	v_mul_f32_e32 v153, 0xbfb8aa3b, v143
	v_mul_f32_e32 v154, 0xbfb8aa3b, v144
	v_mul_f32_e32 v155, 0xbfb8aa3b, v145
	v_exp_f32_e32 v152, v152
	v_exp_f32_e32 v153, v153
	v_exp_f32_e32 v154, v154
	v_exp_f32_e32 v155, v155
	v_add_f32_e32 v152, 1.0, v152
	v_add_f32_e32 v153, 1.0, v153
	v_add_f32_e32 v154, 1.0, v154
	v_add_f32_e32 v155, 1.0, v155
	v_rcp_f32_e32 v152, v152
	v_rcp_f32_e32 v153, v153
	v_rcp_f32_e32 v154, v154
	v_rcp_f32_e32 v155, v155
	v_mul_f32_e32 v156, v138, v142
	v_mul_f32_e32 v157, v139, v143
	v_mul_f32_e32 v158, v140, v144
	v_mul_f32_e32 v159, v141, v145
	v_mul_f32_e32 v156, v156, v152
	v_mul_f32_e32 v157, v157, v153
	v_mul_f32_e32 v158, v158, v154
	v_mul_f32_e32 v159, v159, v155
	v_cvt_pk_bf16_f32 v148, v156, v157
	v_cvt_pk_bf16_f32 v149, v158, v159
	global_store_dwordx2 v48, v[148:149], s[64:65]
	s_add_u32 s64, s64, 0x1600
	s_addc_u32 s65, s65, 0
	s_waitcnt vmcnt(17)
; __device__ __forceinline__ u32x2 pk4(f32x4 v) { u32x2 w; w.x = pk2(v[0], v[1]); w.y = pk2(v[2], v[3]); return w; }
; __device__ __forceinline__ f32x4 ldbf4(const bf16_t* p) { const u32x2 w = *(const u32x2*)p; f32x4 v; v[0] = __uint_as_float(w.x << 16); v[1] = __uint_as_float(w.x & 0xffff0000u); v[2] = __uint_as_float(w.y << 16); v[3] = __uint_as_float(w.y & 0xffff0000u); return v; }
; __device__ __forceinline__ void phase_conv(KP p, int l, int gw, int NGW, int lane) {
;     ...
;     for (int it = gw; it < NRB * 11; it += NGW) {
;         const int rbi = it / 11, sl = it - rbi * 11, rb = NRB - 1 - rbi, r0 = rb * 16, f = sl * 256 + lane * 4;
;         const f32x4 wa0 = *(const f32x4*)(cw + f), wa1 = *(const f32x4*)(cw + DFF2 + f), wa2 = *(const f32x4*)(cw + 2 * DFF2 + f), ba = *(const f32x4*)(cb + f);
;         const f32x4 wg0 = *(const f32x4*)(cw + DFF + f), wg1 = *(const f32x4*)(cw + DFF2 + DFF + f), wg2 = *(const f32x4*)(cw + 2 * DFF2 + DFF + f), bg = *(const f32x4*)(cb + DFF + f);
;         f32x4 a2, a1, g2, g1;
;         if (r0 < RP) { if ((r0 & 4095) == 0) { const bf16_t* m0 = U + (size_t)(RM0 + 14) * DFF2; a2 = ldbf4(m0 + f); g2 = ldbf4(m0 + DFF + f); a1 = ldbf4(m0 + DFF2 + f); g1 = ldbf4(m0 + DFF2 + DFF + f); }
;                        else { const bf16_t* m0 = U + (size_t)(r0 - 2) * DFF2; a2 = ldbf4(m0 + f); g2 = ldbf4(m0 + DFF + f); a1 = ldbf4(m0 + DFF2 + f); g1 = ldbf4(m0 + DFF2 + DFF + f); } }
;         else if (r0 < RS1) { const float* s0 = st + (size_t)((r0 - RS0) >> 4) * 2 * DFF2; a2 = *(const f32x4*)(s0 + f); g2 = *(const f32x4*)(s0 + DFF + f); a1 = *(const f32x4*)(s0 + DFF2 + f); g1 = *(const f32x4*)(s0 + DFF2 + DFF + f); }
;         else { a2 = (f32x4){0.f, 0.f, 0.f, 0.f}; a1 = a2; g2 = a2; g1 = a2; }
; #pragma unroll 4
;         for (int i = 0; i < 16; ++i) { const bf16_t* ur = U + (size_t)(r0 + i) * DFF2; const f32x4 a0 = ldbf4(ur + f), g0 = ldbf4(ur + DFF + f);
;             const f32x4 ca = ba + wa0 * a2 + wa1 * a1 + wa2 * a0, cg = bg + wg0 * g2 + wg1 * g1 + wg2 * g0; f32x4 o;
;             o[0] = ca[0] * cg[0] / (1.f + __expf(-cg[0])); o[1] = ca[1] * cg[1] / (1.f + __expf(-cg[1])); o[2] = ca[2] * cg[2] / (1.f + __expf(-cg[2])); o[3] = ca[3] * cg[3] / (1.f + __expf(-cg[3]));
;             *(u32x2*)(ACT + (size_t)(r0 + i) * DFF + f) = pk4(o);
;             a2 = a1; a1 = a0; g2 = g1; g1 = g0; }
	v_lshlrev_b32_e32 v60, 16, v124
	v_and_b32_e32 v61, 0xffff0000, v124
	v_lshlrev_b32_e32 v62, 16, v125
	v_and_b32_e32 v63, 0xffff0000, v125
	v_lshlrev_b32_e32 v64, 16, v126
	v_and_b32_e32 v65, 0xffff0000, v126
	v_lshlrev_b32_e32 v66, 16, v127
	v_and_b32_e32 v67, 0xffff0000, v127
	v_pk_fma_f32 v[138:139], v[0:1], v[32:33], v[12:13]
	v_pk_fma_f32 v[140:141], v[2:3], v[34:35], v[14:15]
	v_pk_fma_f32 v[142:143], v[16:17], v[36:37], v[28:29]
	v_pk_fma_f32 v[144:145], v[18:19], v[38:39], v[30:31]
	v_pk_fma_f32 v[138:139], v[4:5], v[52:53], v[138:139]
	v_pk_fma_f32 v[140:141], v[6:7], v[54:55], v[140:141]
	v_pk_fma_f32 v[142:143], v[20:21], v[56:57], v[142:143]
	v_pk_fma_f32 v[144:145], v[22:23], v[58:59], v[144:145]
	v_pk_fma_f32 v[138:139], v[8:9], v[60:61], v[138:139]
	v_pk_fma_f32 v[140:141], v[10:11], v[62:63], v[140:141]
	v_pk_fma_f32 v[142:143], v[24:25], v[64:65], v[142:143]
	v_pk_fma_f32 v[144:145], v[26:27], v[66:67], v[144:145]
	v_mul_f32_e32 v152, 0xbfb8aa3b, v142
	v_mul_f32_e32 v153, 0xbfb8aa3b, v143
	v_mul_f32_e32 v154, 0xbfb8aa3b, v144
	v_mul_f32_e32 v155, 0xbfb8aa3b, v145
	v_exp_f32_e32 v152, v152
	v_exp_f32_e32 v153, v153
	v_exp_f32_e32 v154, v154
	v_exp_f32_e32 v155, v155
	v_add_f32_e32 v152, 1.0, v152
	v_add_f32_e32 v153, 1.0, v153
	v_add_f32_e32 v154, 1.0, v154
	v_add_f32_e32 v155, 1.0, v155
	v_rcp_f32_e32 v152, v152
	v_rcp_f32_e32 v153, v153
	v_rcp_f32_e32 v154, v154
	v_rcp_f32_e32 v155, v155
	v_mul_f32_e32 v156, v138, v142
	v_mul_f32_e32 v157, v139, v143
	v_mul_f32_e32 v158, v140, v144
	v_mul_f32_e32 v159, v141, v145
	v_mul_f32_e32 v156, v156, v152
	v_mul_f32_e32 v157, v157, v153
	v_mul_f32_e32 v158, v158, v154
	v_mul_f32_e32 v159, v159, v155
	v_cvt_pk_bf16_f32 v68, v156, v157
	v_cvt_pk_bf16_f32 v69, v158, v159
	global_store_dwordx2 v48, v[68:69], s[64:65]
	s_add_u32 s64, s64, 0x1600
	s_addc_u32 s65, s65, 0
	s_waitcnt vmcnt(16)
	v_lshlrev_b32_e32 v44, 16, v130
	v_and_b32_e32 v45, 0xffff0000, v130
	v_lshlrev_b32_e32 v46, 16, v131
	v_and_b32_e32 v47, 0xffff0000, v131
	v_lshlrev_b32_e32 v40, 16, v132
	v_and_b32_e32 v41, 0xffff0000, v132
	v_lshlrev_b32_e32 v42, 16, v133
	v_and_b32_e32 v43, 0xffff0000, v133
	v_pk_fma_f32 v[138:139], v[0:1], v[52:53], v[12:13]
	v_pk_fma_f32 v[140:141], v[2:3], v[54:55], v[14:15]
	v_pk_fma_f32 v[142:143], v[16:17], v[56:57], v[28:29]
	v_pk_fma_f32 v[144:145], v[18:19], v[58:59], v[30:31]
	v_pk_fma_f32 v[138:139], v[4:5], v[60:61], v[138:139]
	v_pk_fma_f32 v[140:141], v[6:7], v[62:63], v[140:141]
	v_pk_fma_f32 v[142:143], v[20:21], v[64:65], v[142:143]
	v_pk_fma_f32 v[144:145], v[22:23], v[66:67], v[144:145]
	v_pk_fma_f32 v[138:139], v[8:9], v[44:45], v[138:139]
	v_pk_fma_f32 v[140:141], v[10:11], v[46:47], v[140:141]
	v_pk_fma_f32 v[142:143], v[24:25], v[40:41], v[142:143]
	v_pk_fma_f32 v[144:145], v[26:27], v[42:43], v[144:145]
	v_mul_f32_e32 v152, 0xbfb8aa3b, v142
	v_mul_f32_e32 v153, 0xbfb8aa3b, v143
	v_mul_f32_e32 v154, 0xbfb8aa3b, v144
	v_mul_f32_e32 v155, 0xbfb8aa3b, v145
	v_exp_f32_e32 v152, v152
	v_exp_f32_e32 v153, v153
	v_exp_f32_e32 v154, v154
	v_exp_f32_e32 v155, v155
	v_add_f32_e32 v152, 1.0, v152
	v_add_f32_e32 v153, 1.0, v153
	v_add_f32_e32 v154, 1.0, v154
	v_add_f32_e32 v155, 1.0, v155
	v_rcp_f32_e32 v152, v152
	v_rcp_f32_e32 v153, v153
	v_rcp_f32_e32 v154, v154
	v_rcp_f32_e32 v155, v155
	v_mul_f32_e32 v156, v138, v142
	v_mul_f32_e32 v157, v139, v143
	v_mul_f32_e32 v158, v140, v144
	v_mul_f32_e32 v159, v141, v145
	v_mul_f32_e32 v156, v156, v152
	v_mul_f32_e32 v157, v157, v153
	v_mul_f32_e32 v158, v158, v154
	v_mul_f32_e32 v159, v159, v155
	v_cvt_pk_bf16_f32 v148, v156, v157
	v_cvt_pk_bf16_f32 v149, v158, v159
	global_store_dwordx2 v48, v[148:149], s[64:65]
	s_add_u32 s64, s64, 0x1600
	s_addc_u32 s65, s65, 0
	s_waitcnt vmcnt(15)
	v_lshlrev_b32_e32 v32, 16, v134
	v_and_b32_e32 v33, 0xffff0000, v134
	v_lshlrev_b32_e32 v34, 16, v135
	v_and_b32_e32 v35, 0xffff0000, v135
	v_lshlrev_b32_e32 v36, 16, v136
	v_and_b32_e32 v37, 0xffff0000, v136
	v_lshlrev_b32_e32 v38, 16, v137
	v_and_b32_e32 v39, 0xffff0000, v137
	v_pk_fma_f32 v[138:139], v[0:1], v[60:61], v[12:13]
	v_pk_fma_f32 v[140:141], v[2:3], v[62:63], v[14:15]
	v_pk_fma_f32 v[142:143], v[16:17], v[64:65], v[28:29]
	v_pk_fma_f32 v[144:145], v[18:19], v[66:67], v[30:31]
	v_pk_fma_f32 v[138:139], v[4:5], v[44:45], v[138:139]
	v_pk_fma_f32 v[140:141], v[6:7], v[46:47], v[140:141]
	v_pk_fma_f32 v[142:143], v[20:21], v[40:41], v[142:143]
	v_pk_fma_f32 v[144:145], v[22:23], v[42:43], v[144:145]
	v_pk_fma_f32 v[138:139], v[8:9], v[32:33], v[138:139]
	v_pk_fma_f32 v[140:141], v[10:11], v[34:35], v[140:141]
	v_pk_fma_f32 v[142:143], v[24:25], v[36:37], v[142:143]
	v_pk_fma_f32 v[144:145], v[26:27], v[38:39], v[144:145]
	v_mul_f32_e32 v152, 0xbfb8aa3b, v142
	v_mul_f32_e32 v153, 0xbfb8aa3b, v143
	v_mul_f32_e32 v154, 0xbfb8aa3b, v144
	v_mul_f32_e32 v155, 0xbfb8aa3b, v145
	v_exp_f32_e32 v152, v152
	v_exp_f32_e32 v153, v153
	v_exp_f32_e32 v154, v154
	v_exp_f32_e32 v155, v155
	v_add_f32_e32 v152, 1.0, v152
	v_add_f32_e32 v153, 1.0, v153
	v_add_f32_e32 v154, 1.0, v154
	v_add_f32_e32 v155, 1.0, v155
	v_rcp_f32_e32 v152, v152
	v_rcp_f32_e32 v153, v153
	v_rcp_f32_e32 v154, v154
	v_rcp_f32_e32 v155, v155
	v_mul_f32_e32 v156, v138, v142
	v_mul_f32_e32 v157, v139, v143
	v_mul_f32_e32 v158, v140, v144
	v_mul_f32_e32 v159, v141, v145
	v_mul_f32_e32 v156, v156, v152
	v_mul_f32_e32 v157, v157, v153
	v_mul_f32_e32 v158, v158, v154
	v_mul_f32_e32 v159, v159, v155
	v_cvt_pk_bf16_f32 v68, v156, v157
	v_cvt_pk_bf16_f32 v69, v158, v159
	global_store_dwordx2 v48, v[68:69], s[64:65]
	s_add_i32 s15, s15, s70
	s_cmpk_gt_i32 s15, 0x5862
	v_add_u32_e32 v71, s91, v71
	s_cbranch_scc0 .LBB0_1368
	v_readlane_b32 s60, v255, 0
	v_readlane_b32 s62, v255, 2
	v_readlane_b32 s52, v255, 4
	v_readlane_b32 s54, v255, 6
	v_readlane_b32 s50, v255, 8
	v_readlane_b32 s56, v255, 20
	v_readlane_b32 s61, v255, 1
	v_readlane_b32 s63, v255, 3
	v_readlane_b32 s53, v255, 5
	v_readlane_b32 s55, v255, 7
	v_readlane_b32 s51, v255, 9
	v_readlane_b32 s57, v255, 21
	v_readlane_b32 s59, v255, 23
